# G1/G3/G4 K-loops rewritten: K=64 line-shaped LDS-DMA (8 rows x 128 B per instruction), N-split phases, A fragments kept across phases
# speedup vs baseline: 1.0316x; 1.0316x over previous
.LBB0_79:
	s_and_b32 s4, 0xffff, s56
	s_mul_hi_u32 s4, s4, 0x2492493
	s_lshl_b32 s5, s4, 3
	v_readlane_b32 s7, v254, 25
	s_add_i32 s5, s7, s5
	s_and_b32 s6, s55, 7
	s_add_i32 s21, s5, s6
	s_bfe_u32 s6, s57, 0x100004
	s_mulk_i32 s6, 0x2493
	s_lshr_b32 s6, s6, 16
	v_mov_b32_e32 v153, v179
	s_mul_i32 s48, s6, 0xffffff90
	s_lshl_b32 s6, s6, 3
	s_add_i32 s6, s6, s7
	v_readfirstlane_b32 s37, v153
	s_and_b32 s7, s57, 7
	s_ashr_i32 s15, s37, 6
	v_and_b32_e32 v1, 60, v153
	s_mulk_i32 s4, 0xe00
	s_add_i32 s48, s48, s57
	s_or_b32 s6, s6, s7
	v_lshl_or_b32 v1, s15, 7, v1
	s_sub_i32 s4, s54, s4
	s_lshl_b32 s10, s6, 7
	s_lshl_b32 s90, s48, 5
	v_bfe_u32 v13, v153, 2, 4
	s_and_b32 s6, s37, 0x3fffc0
	v_ashrrev_i32_e32 v17, 2, v1
	s_and_b32 s4, s4, 0xffffff00
	s_and_b32 s8, s90, 0xffffff00
	v_lshrrev_b32_e32 v12, 4, v153
	v_or_b32_e32 v2, s6, v13
	s_lshl_b32 s6, s15, 11
	s_waitcnt vmcnt(0)
	v_add_u32_e32 v8, s10, v17
	s_ashr_i32 s5, s4, 31
	v_xor_b32_e32 v0, v12, v153
	s_add_i32 s13, s6, 16
	v_ashrrev_i32_e32 v9, 31, v8
	s_ashr_i32 s9, s8, 31
	s_lshl_b64 s[4:5], s[4:5], 11
	s_ashr_i32 s11, s37, 7
	s_and_b32 s12, s15, 1
	v_lshlrev_b32_e32 v0, 3, v0
	v_lshlrev_b64 v[10:11], 11, v[8:9]
	v_or_b32_e32 v8, 16, v8
	s_add_i32 s14, s13, 0x400
	s_lshl_b64 s[6:7], s[8:9], 11
	v_and_b32_e32 v14, 24, v0
	v_ashrrev_i32_e32 v9, 31, v8
	s_add_u32 s6, s52, s6
	v_lshl_add_u64 v[10:11], s[80:81], 0, v[10:11]
	v_lshlrev_b32_e32 v176, 1, v14
	v_lshlrev_b64 v[8:9], 11, v[8:9]
	s_addc_u32 s7, s53, s7
	s_lshl_b32 s9, s15, 12
	v_lshl_or_b32 v0, v2, 10, v14
	v_lshl_add_u64 v[10:11], v[10:11], 0, v[176:177]
	s_mov_b32 m0, s13
	v_lshl_add_u64 v[8:9], s[80:81], 0, v[8:9]
	s_add_i32 s9, s9, 16
	v_or_b32_e32 v2, 0x4000, v0
	v_bfe_u32 v152, v153, 5, 1
	v_lshrrev_b32_e32 v3, 2, v153
	v_lshl_add_u64 v[8:9], v[8:9], 0, v[176:177]
	s_mov_b32 m0, s14
	s_add_i32 s15, s9, 0x2000
	v_ashrrev_i32_e32 v1, 31, v0
	v_or_b32_e32 v4, 0x8000, v0
	v_or_b32_e32 v6, 0xc000, v0
	v_bfe_u32 v5, v153, 2, 2
	v_bitop3_b32 v15, v152, v3, 3 bitop3:0x78
	v_lshl_add_u64 v[0:1], v[0:1], 1, s[6:7]
	s_mov_b32 m0, s15
	v_ashrrev_i32_e32 v3, 31, v2
	s_add_i32 s16, s9, 0x2400
	v_bitop3_b32 v16, v152, v5, 2 bitop3:0x36
	v_lshl_add_u64 v[0:1], v[2:3], 1, s[6:7]
	s_mov_b32 m0, s16
	v_ashrrev_i32_e32 v5, 31, v4
	s_add_i32 s17, s9, 0x2800
	v_lshl_add_u64 v[0:1], v[4:5], 1, s[6:7]
	s_mov_b32 m0, s17
	v_ashrrev_i32_e32 v7, 31, v6
	s_add_i32 s20, s9, 0x2c00
	v_lshl_add_u64 v[0:1], v[6:7], 1, s[6:7]
	s_mov_b32 m0, s20
	s_lshl_b32 s6, s12, 13
	v_lshl_add_u32 v0, v15, 4, 16
	s_lshl_b32 s7, s11, 12
	v_add_u32_e32 v5, s7, v0
	v_add_u32_e32 v6, s6, v0
	v_lshl_add_u32 v0, v16, 4, 16
	v_add_u32_e32 v7, s7, v0
	v_add_u32_e32 v8, s6, v0
	v_lshl_add_u32 v0, s21, 7, v17
	v_ashrrev_i32_e32 v1, 31, v0
	v_lshlrev_b64 v[2:3], 11, v[0:1]
	v_bitop3_b32 v1, v12, 3, v153 bitop3:0x48
	v_or_b32_e32 v0, 16, v0
	v_lshlrev_b32_e32 v9, 4, v1
	v_ashrrev_i32_e32 v1, 31, v0
	v_lshlrev_b64 v[0:1], 11, v[0:1]
	v_or_b32_e32 v0, v0, v9
	s_lshl_b32 s6, s37, 10
	v_lshl_add_u64 v[130:131], s[80:81], 0, v[0:1]
	s_and_b32 s6, s6, 0xffff0000
	v_lshlrev_b32_e32 v0, 10, v13
	v_or_b32_e32 v2, v2, v9
	v_or3_b32 v0, v0, s6, v14
	v_lshl_add_u64 v[128:129], s[80:81], 0, v[2:3]
	s_add_u32 s4, s52, s4
	v_or_b32_e32 v2, 0x4000, v0
	v_ashrrev_i32_e32 v1, 31, v0
	s_addc_u32 s5, s53, s5
	v_ashrrev_i32_e32 v3, 31, v2
	v_and_b32_e32 v169, 31, v153
	v_lshl_add_u64 v[132:133], v[0:1], 1, s[4:5]
	v_lshl_add_u64 v[134:135], v[2:3], 1, s[4:5]
	v_or_b32_e32 v2, 0x8000, v0
	v_or_b32_e32 v0, 0xc000, v0
	v_lshlrev_b32_e32 v4, 6, v169
	v_ashrrev_i32_e32 v3, 31, v2
	v_ashrrev_i32_e32 v1, 31, v0
	v_mov_b32_e32 v96, 0
	v_lshl_add_u64 v[136:137], v[2:3], 1, s[4:5]
	v_lshl_add_u64 v[138:139], v[0:1], 1, s[4:5]
	s_mov_b32 s21, 0
	s_mov_b64 s[4:5], 0
	v_add_u32_e32 v154, v5, v4
	v_add_u32_e32 v155, v6, v4
	v_add_u32_e32 v156, v7, v4
	v_add_u32_e32 v157, v8, v4
	v_mov_b32_e32 v97, v96
	v_mov_b32_e32 v98, v96
	v_mov_b32_e32 v99, v96
	v_mov_b32_e32 v100, v96
	v_mov_b32_e32 v101, v96
	v_mov_b32_e32 v102, v96
	v_mov_b32_e32 v103, v96
	v_mov_b32_e32 v104, v96
	v_mov_b32_e32 v105, v96
	v_mov_b32_e32 v106, v96
	v_mov_b32_e32 v107, v96
	v_mov_b32_e32 v108, v96
	v_mov_b32_e32 v109, v96
	v_mov_b32_e32 v110, v96
	v_mov_b32_e32 v111, v96
	v_mov_b32_e32 v80, v96
	v_mov_b32_e32 v81, v96
	v_mov_b32_e32 v82, v96
	v_mov_b32_e32 v83, v96
	v_mov_b32_e32 v84, v96
	v_mov_b32_e32 v85, v96
	v_mov_b32_e32 v86, v96
	v_mov_b32_e32 v87, v96
	v_mov_b32_e32 v88, v96
	v_mov_b32_e32 v89, v96
	v_mov_b32_e32 v90, v96
	v_mov_b32_e32 v91, v96
	v_mov_b32_e32 v92, v96
	v_mov_b32_e32 v93, v96
	v_mov_b32_e32 v94, v96
	v_mov_b32_e32 v95, v96
	v_mov_b32_e32 v48, v96
	v_mov_b32_e32 v49, v96
	v_mov_b32_e32 v50, v96
	v_mov_b32_e32 v51, v96
	v_mov_b32_e32 v52, v96
	v_mov_b32_e32 v53, v96
	v_mov_b32_e32 v54, v96
	v_mov_b32_e32 v55, v96
	v_mov_b32_e32 v56, v96
	v_mov_b32_e32 v57, v96
	v_mov_b32_e32 v58, v96
	v_mov_b32_e32 v59, v96
	v_mov_b32_e32 v60, v96
	v_mov_b32_e32 v61, v96
	v_mov_b32_e32 v62, v96
	v_mov_b32_e32 v63, v96
	v_mov_b32_e32 v16, v96
	v_mov_b32_e32 v17, v96
	v_mov_b32_e32 v18, v96
	v_mov_b32_e32 v19, v96
	v_mov_b32_e32 v20, v96
	v_mov_b32_e32 v21, v96
	v_mov_b32_e32 v22, v96
	v_mov_b32_e32 v23, v96
	v_mov_b32_e32 v24, v96
	v_mov_b32_e32 v25, v96
	v_mov_b32_e32 v26, v96
	v_mov_b32_e32 v27, v96
	v_mov_b32_e32 v28, v96
	v_mov_b32_e32 v29, v96
	v_mov_b32_e32 v30, v96
	v_mov_b32_e32 v31, v96
	v_mov_b32_e32 v112, v96
	v_mov_b32_e32 v113, v96
	v_mov_b32_e32 v114, v96
	v_mov_b32_e32 v115, v96
	v_mov_b32_e32 v116, v96
	v_mov_b32_e32 v117, v96
	v_mov_b32_e32 v118, v96
	v_mov_b32_e32 v119, v96
	v_mov_b32_e32 v120, v96
	v_mov_b32_e32 v121, v96
	v_mov_b32_e32 v122, v96
	v_mov_b32_e32 v123, v96
	v_mov_b32_e32 v124, v96
	v_mov_b32_e32 v125, v96
	v_mov_b32_e32 v126, v96
	v_mov_b32_e32 v127, v96
	v_mov_b32_e32 v64, v96
	v_mov_b32_e32 v65, v96
	v_mov_b32_e32 v66, v96
	v_mov_b32_e32 v67, v96
	v_mov_b32_e32 v68, v96
	v_mov_b32_e32 v69, v96
	v_mov_b32_e32 v70, v96
	v_mov_b32_e32 v71, v96
	v_mov_b32_e32 v72, v96
	v_mov_b32_e32 v73, v96
	v_mov_b32_e32 v74, v96
	v_mov_b32_e32 v75, v96
	v_mov_b32_e32 v76, v96
	v_mov_b32_e32 v77, v96
	v_mov_b32_e32 v78, v96
	v_mov_b32_e32 v79, v96
	v_mov_b32_e32 v32, v96
	v_mov_b32_e32 v33, v96
	v_mov_b32_e32 v34, v96
	v_mov_b32_e32 v35, v96
	v_mov_b32_e32 v36, v96
	v_mov_b32_e32 v37, v96
	v_mov_b32_e32 v38, v96
	v_mov_b32_e32 v39, v96
	v_mov_b32_e32 v40, v96
	v_mov_b32_e32 v41, v96
	v_mov_b32_e32 v42, v96
	v_mov_b32_e32 v43, v96
	v_mov_b32_e32 v44, v96
	v_mov_b32_e32 v45, v96
	v_mov_b32_e32 v46, v96
	v_mov_b32_e32 v47, v96
	v_mov_b32_e32 v0, v96
	v_mov_b32_e32 v1, v96
	v_mov_b32_e32 v2, v96
	v_mov_b32_e32 v3, v96
	v_mov_b32_e32 v4, v96
	v_mov_b32_e32 v5, v96
	v_mov_b32_e32 v6, v96
	v_mov_b32_e32 v7, v96
	v_mov_b32_e32 v8, v96
	v_mov_b32_e32 v9, v96
	v_mov_b32_e32 v10, v96
	v_mov_b32_e32 v11, v96
	v_mov_b32_e32 v12, v96
	v_mov_b32_e32 v13, v96
	v_mov_b32_e32 v14, v96
	v_mov_b32_e32 v15, v96
	v_and_b32_e32 v158, 63, v153
	v_readfirstlane_b32 s9, v179
	v_readfirstlane_b32 s18, v128
	v_readfirstlane_b32 s19, v129
	v_readfirstlane_b32 s20, v132
	v_readfirstlane_b32 s21, v133
	s_lshr_b32 s9, s9, 6
	s_mul_i32 s59, s9, 0x8000
	s_sub_u32 s18, s18, s59
	s_subb_u32 s19, s19, 0
	s_and_b32 s59, s9, 1
	s_mul_i32 s59, s59, 0x10000
	s_sub_u32 s20, s20, s59
	s_subb_u32 s21, s21, 0
	s_mov_b32 s49, 0x800
	v_and_b32_e32 v140, 63, v179
	v_lshrrev_b32_e32 v141, 3, v140
	v_lshrrev_b32_e32 v143, 4, v140
	v_and_b32_e32 v142, 7, v140
	v_xor_b32_e32 v142, v142, v143
	v_lshlrev_b32_e32 v142, 4, v142
	v_mad_u32_u24 v176, v141, s49, v142
	v_lshl_add_u64 v[128:129], s[18:19], 0, v[176:177]
	v_lshl_add_u64 v[132:133], s[20:21], 0, v[176:177]
	v_xor_b32_e32 v142, 64, v142
	v_mad_u32_u24 v176, v141, s49, v142
	s_add_u32 s50, s18, 0x4000
	s_addc_u32 s51, s19, 0
	v_lshl_add_u64 v[130:131], s[50:51], 0, v[176:177]
	s_add_u32 s50, s20, 0x4000
	s_addc_u32 s51, s21, 0
	s_nop 0
	v_lshl_add_u64 v[134:135], s[50:51], 0, v[176:177]
	v_and_b32_e32 v144, 31, v179
	v_bfe_u32 v145, v179, 5, 1
	v_bfe_u32 v143, v179, 1, 3
	v_xor_b32_e32 v145, v145, v143
	s_lshr_b32 s59, s9, 1
	s_lshl_b32 s59, s59, 13
	s_add_i32 s59, s59, 16
	v_lshl_add_u32 v146, v144, 7, s59
	s_and_b32 s59, s9, 1
	s_lshl_b32 s59, s59, 13
	s_add_i32 s59, s59, 16
	v_lshl_add_u32 v147, v144, 7, s59
	v_xor_b32_e32 v143, 0, v145
	v_lshl_add_u32 v136, v143, 4, v146
	v_lshl_add_u32 v232, v143, 4, v147
	v_xor_b32_e32 v143, 2, v145
	v_lshl_add_u32 v137, v143, 4, v146
	v_lshl_add_u32 v233, v143, 4, v147
	v_xor_b32_e32 v143, 4, v145
	v_lshl_add_u32 v138, v143, 4, v146
	v_lshl_add_u32 v237, v143, 4, v147
	v_xor_b32_e32 v143, 6, v145
	v_lshl_add_u32 v139, v143, 4, v146
	v_lshl_add_u32 v252, v143, 4, v147
	s_lshl_b32 s13, s9, 11
	s_add_i32 s13, s13, 16
	s_lshl_b32 s32, s9, 12
	s_add_i32 s32, s32, 16
	s_mov_b64 s[4:5], 0
	s_mov_b64 s[6:7], 0x80
	s_mov_b32 s14, 0x20000
	s_mov_b32 s15, 0
	s_mov_b32 s16, 0x8000
	s_mov_b32 s17, 0
	s_add_i32 m0, s13, 0x0
	s_nop 0
	global_load_lds_dwordx4 v[128:129], off
	s_add_i32 m0, s13, 0x400
	s_nop 0
	global_load_lds_dwordx4 v[130:131], off
	v_lshl_add_u64 v[246:247], v[128:129], 0, s[14:15]
	s_add_i32 m0, s13, 0x2000
	s_nop 0
	global_load_lds_dwordx4 v[246:247], off
	v_lshl_add_u64 v[248:249], v[130:131], 0, s[14:15]
	s_add_i32 m0, s13, 0x2400
	s_nop 0
	global_load_lds_dwordx4 v[248:249], off
	s_add_i32 m0, s32, 0x8000
	s_nop 0
	global_load_lds_dwordx4 v[132:133], off
	s_add_i32 m0, s32, 0x8400
	s_nop 0
	global_load_lds_dwordx4 v[134:135], off
	v_lshl_add_u64 v[246:247], v[132:133], 0, s[16:17]
	s_add_i32 m0, s32, 0x8800
	s_nop 0
	global_load_lds_dwordx4 v[246:247], off
	v_lshl_add_u64 v[248:249], v[134:135], 0, s[16:17]
	s_add_i32 m0, s32, 0x8c00
	s_nop 0
	global_load_lds_dwordx4 v[248:249], off
	s_movk_i32 s37, 7
.Lk1_loop:
	s_waitcnt vmcnt(0)
	s_barrier
	ds_read_b128 v[140:143], v136 offset:0
	ds_read_b128 v[188:191], v232 offset:32768
	ds_read_b128 v[204:207], v232 offset:36864
	ds_read_b128 v[164:167], v136 offset:4096
	ds_read_b128 v[144:147], v137 offset:0
	ds_read_b128 v[192:195], v233 offset:32768
	ds_read_b128 v[208:211], v233 offset:36864
	ds_read_b128 v[170:173], v137 offset:4096
	v_lshl_add_u64 v[246:247], v[132:133], 0, s[4:5]
	v_lshl_add_u64 v[246:247], v[246:247], 0, s[14:15]
	s_add_i32 m0, s32, 0xc000
	s_nop 0
	global_load_lds_dwordx4 v[246:247], off
	v_lshl_add_u64 v[248:249], v[134:135], 0, s[4:5]
	v_lshl_add_u64 v[248:249], v[248:249], 0, s[14:15]
	s_add_i32 m0, s32, 0xc400
	s_nop 0
	global_load_lds_dwordx4 v[248:249], off
	v_lshl_add_u64 v[246:247], v[132:133], 0, s[4:5]
	v_lshl_add_u64 v[246:247], v[246:247], 0, s[14:15]
	v_lshl_add_u64 v[246:247], v[246:247], 0, s[16:17]
	s_add_i32 m0, s32, 0xc800
	s_nop 0
	global_load_lds_dwordx4 v[246:247], off
	v_lshl_add_u64 v[248:249], v[134:135], 0, s[4:5]
	v_lshl_add_u64 v[248:249], v[248:249], 0, s[14:15]
	v_lshl_add_u64 v[248:249], v[248:249], 0, s[16:17]
	s_add_i32 m0, s32, 0xcc00
	s_nop 0
	global_load_lds_dwordx4 v[248:249], off
	v_lshl_add_u64 v[246:247], v[128:129], 0, s[6:7]
	s_add_i32 m0, s13, 0x4000
	s_nop 0
	global_load_lds_dwordx4 v[246:247], off
	v_lshl_add_u64 v[248:249], v[130:131], 0, s[6:7]
	s_add_i32 m0, s13, 0x4400
	s_nop 0
	global_load_lds_dwordx4 v[248:249], off
	s_setprio 1
	s_waitcnt lgkmcnt(6)
	v_mfma_f32_32x32x16_bf16 v[96:111], v[188:191], v[140:143], v[96:111]
	s_waitcnt lgkmcnt(5)
	v_mfma_f32_32x32x16_bf16 v[80:95], v[204:207], v[140:143], v[80:95]
	s_waitcnt lgkmcnt(4)
	v_mfma_f32_32x32x16_bf16 v[112:127], v[188:191], v[164:167], v[112:127]
	v_mfma_f32_32x32x16_bf16 v[64:79], v[204:207], v[164:167], v[64:79]
	ds_read_b128 v[148:151], v138 offset:0
	ds_read_b128 v[196:199], v237 offset:32768
	ds_read_b128 v[238:241], v237 offset:36864
	ds_read_b128 v[180:183], v138 offset:4096
	s_waitcnt lgkmcnt(6)
	v_mfma_f32_32x32x16_bf16 v[96:111], v[192:195], v[144:147], v[96:111]
	s_waitcnt lgkmcnt(5)
	v_mfma_f32_32x32x16_bf16 v[80:95], v[208:211], v[144:147], v[80:95]
	s_waitcnt lgkmcnt(4)
	v_mfma_f32_32x32x16_bf16 v[112:127], v[192:195], v[170:173], v[112:127]
	v_mfma_f32_32x32x16_bf16 v[64:79], v[208:211], v[170:173], v[64:79]
	ds_read_b128 v[160:163], v139 offset:0
	ds_read_b128 v[200:203], v252 offset:32768
	ds_read_b128 v[242:245], v252 offset:36864
	ds_read_b128 v[184:187], v139 offset:4096
	s_waitcnt lgkmcnt(6)
	v_mfma_f32_32x32x16_bf16 v[96:111], v[196:199], v[148:151], v[96:111]
	s_waitcnt lgkmcnt(5)
	v_mfma_f32_32x32x16_bf16 v[80:95], v[238:241], v[148:151], v[80:95]
	s_waitcnt lgkmcnt(4)
	v_mfma_f32_32x32x16_bf16 v[112:127], v[196:199], v[180:183], v[112:127]
	v_mfma_f32_32x32x16_bf16 v[64:79], v[238:241], v[180:183], v[64:79]
	s_waitcnt lgkmcnt(2)
	v_mfma_f32_32x32x16_bf16 v[96:111], v[200:203], v[160:163], v[96:111]
	s_waitcnt lgkmcnt(1)
	v_mfma_f32_32x32x16_bf16 v[80:95], v[242:245], v[160:163], v[80:95]
	s_waitcnt lgkmcnt(0)
	v_mfma_f32_32x32x16_bf16 v[112:127], v[200:203], v[184:187], v[112:127]
	v_mfma_f32_32x32x16_bf16 v[64:79], v[242:245], v[184:187], v[64:79]
	s_setprio 0
	s_waitcnt vmcnt(2)
	s_barrier
	ds_read_b128 v[188:191], v232 offset:49152
	ds_read_b128 v[204:207], v232 offset:53248
	ds_read_b128 v[192:195], v233 offset:49152
	ds_read_b128 v[208:211], v233 offset:53248
	ds_read_b128 v[196:199], v237 offset:49152
	ds_read_b128 v[238:241], v237 offset:53248
	ds_read_b128 v[200:203], v252 offset:49152
	ds_read_b128 v[242:245], v252 offset:53248
	v_lshl_add_u64 v[246:247], v[132:133], 0, s[6:7]
	s_add_i32 m0, s32, 0x8000
	s_nop 0
	global_load_lds_dwordx4 v[246:247], off
	v_lshl_add_u64 v[248:249], v[134:135], 0, s[6:7]
	s_add_i32 m0, s32, 0x8400
	s_nop 0
	global_load_lds_dwordx4 v[248:249], off
	v_lshl_add_u64 v[246:247], v[132:133], 0, s[6:7]
	v_lshl_add_u64 v[246:247], v[246:247], 0, s[16:17]
	s_add_i32 m0, s32, 0x8800
	s_nop 0
	global_load_lds_dwordx4 v[246:247], off
	v_lshl_add_u64 v[248:249], v[134:135], 0, s[6:7]
	v_lshl_add_u64 v[248:249], v[248:249], 0, s[16:17]
	s_add_i32 m0, s32, 0x8c00
	s_nop 0
	global_load_lds_dwordx4 v[248:249], off
	v_lshl_add_u64 v[246:247], v[128:129], 0, s[6:7]
	v_lshl_add_u64 v[246:247], v[246:247], 0, s[14:15]
	s_add_i32 m0, s13, 0x6000
	s_nop 0
	global_load_lds_dwordx4 v[246:247], off
	v_lshl_add_u64 v[248:249], v[130:131], 0, s[6:7]
	v_lshl_add_u64 v[248:249], v[248:249], 0, s[14:15]
	s_add_i32 m0, s13, 0x6400
	s_nop 0
	global_load_lds_dwordx4 v[248:249], off
	s_add_u32 s4, s4, 0x80
	s_addc_u32 s5, s5, 0
	s_add_u32 s6, s6, 0x80
	s_addc_u32 s7, s7, 0
	s_setprio 1
	s_waitcnt lgkmcnt(7)
	v_mfma_f32_32x32x16_bf16 v[48:63], v[188:191], v[140:143], v[48:63]
	s_waitcnt lgkmcnt(6)
	v_mfma_f32_32x32x16_bf16 v[16:31], v[204:207], v[140:143], v[16:31]
	v_mfma_f32_32x32x16_bf16 v[32:47], v[188:191], v[164:167], v[32:47]
	v_mfma_f32_32x32x16_bf16 v[0:15], v[204:207], v[164:167], v[0:15]
	s_waitcnt lgkmcnt(5)
	v_mfma_f32_32x32x16_bf16 v[48:63], v[192:195], v[144:147], v[48:63]
	s_waitcnt lgkmcnt(4)
	v_mfma_f32_32x32x16_bf16 v[16:31], v[208:211], v[144:147], v[16:31]
	v_mfma_f32_32x32x16_bf16 v[32:47], v[192:195], v[170:173], v[32:47]
	v_mfma_f32_32x32x16_bf16 v[0:15], v[208:211], v[170:173], v[0:15]
	s_waitcnt lgkmcnt(3)
	v_mfma_f32_32x32x16_bf16 v[48:63], v[196:199], v[148:151], v[48:63]
	s_waitcnt lgkmcnt(2)
	v_mfma_f32_32x32x16_bf16 v[16:31], v[238:241], v[148:151], v[16:31]
	v_mfma_f32_32x32x16_bf16 v[32:47], v[196:199], v[180:183], v[32:47]
	v_mfma_f32_32x32x16_bf16 v[0:15], v[238:241], v[180:183], v[0:15]
	s_waitcnt lgkmcnt(1)
	v_mfma_f32_32x32x16_bf16 v[48:63], v[200:203], v[160:163], v[48:63]
	s_waitcnt lgkmcnt(0)
	v_mfma_f32_32x32x16_bf16 v[16:31], v[242:245], v[160:163], v[16:31]
	v_mfma_f32_32x32x16_bf16 v[32:47], v[200:203], v[184:187], v[32:47]
	v_mfma_f32_32x32x16_bf16 v[0:15], v[242:245], v[184:187], v[0:15]
	s_setprio 0
	s_waitcnt vmcnt(0)
	s_barrier
	ds_read_b128 v[140:143], v136 offset:16384
	ds_read_b128 v[188:191], v232 offset:32768
	ds_read_b128 v[204:207], v232 offset:36864
	ds_read_b128 v[164:167], v136 offset:20480
	ds_read_b128 v[144:147], v137 offset:16384
	ds_read_b128 v[192:195], v233 offset:32768
	ds_read_b128 v[208:211], v233 offset:36864
	ds_read_b128 v[170:173], v137 offset:20480
	v_lshl_add_u64 v[246:247], v[132:133], 0, s[4:5]
	v_lshl_add_u64 v[246:247], v[246:247], 0, s[14:15]
	s_add_i32 m0, s32, 0xc000
	s_nop 0
	global_load_lds_dwordx4 v[246:247], off
	v_lshl_add_u64 v[248:249], v[134:135], 0, s[4:5]
	v_lshl_add_u64 v[248:249], v[248:249], 0, s[14:15]
	s_add_i32 m0, s32, 0xc400
	s_nop 0
	global_load_lds_dwordx4 v[248:249], off
	v_lshl_add_u64 v[246:247], v[132:133], 0, s[4:5]
	v_lshl_add_u64 v[246:247], v[246:247], 0, s[14:15]
	v_lshl_add_u64 v[246:247], v[246:247], 0, s[16:17]
	s_add_i32 m0, s32, 0xc800
	s_nop 0
	global_load_lds_dwordx4 v[246:247], off
	v_lshl_add_u64 v[248:249], v[134:135], 0, s[4:5]
	v_lshl_add_u64 v[248:249], v[248:249], 0, s[14:15]
	v_lshl_add_u64 v[248:249], v[248:249], 0, s[16:17]
	s_add_i32 m0, s32, 0xcc00
	s_nop 0
	global_load_lds_dwordx4 v[248:249], off
	v_lshl_add_u64 v[246:247], v[128:129], 0, s[6:7]
	s_add_i32 m0, s13, 0x0
	s_nop 0
	global_load_lds_dwordx4 v[246:247], off
	v_lshl_add_u64 v[248:249], v[130:131], 0, s[6:7]
	s_add_i32 m0, s13, 0x400
	s_nop 0
	global_load_lds_dwordx4 v[248:249], off
	s_setprio 1
	s_waitcnt lgkmcnt(6)
	v_mfma_f32_32x32x16_bf16 v[96:111], v[188:191], v[140:143], v[96:111]
	s_waitcnt lgkmcnt(5)
	v_mfma_f32_32x32x16_bf16 v[80:95], v[204:207], v[140:143], v[80:95]
	s_waitcnt lgkmcnt(4)
	v_mfma_f32_32x32x16_bf16 v[112:127], v[188:191], v[164:167], v[112:127]
	v_mfma_f32_32x32x16_bf16 v[64:79], v[204:207], v[164:167], v[64:79]
	ds_read_b128 v[148:151], v138 offset:16384
	ds_read_b128 v[196:199], v237 offset:32768
	ds_read_b128 v[238:241], v237 offset:36864
	ds_read_b128 v[180:183], v138 offset:20480
	s_waitcnt lgkmcnt(6)
	v_mfma_f32_32x32x16_bf16 v[96:111], v[192:195], v[144:147], v[96:111]
	s_waitcnt lgkmcnt(5)
	v_mfma_f32_32x32x16_bf16 v[80:95], v[208:211], v[144:147], v[80:95]
	s_waitcnt lgkmcnt(4)
	v_mfma_f32_32x32x16_bf16 v[112:127], v[192:195], v[170:173], v[112:127]
	v_mfma_f32_32x32x16_bf16 v[64:79], v[208:211], v[170:173], v[64:79]
	ds_read_b128 v[160:163], v139 offset:16384
	ds_read_b128 v[200:203], v252 offset:32768
	ds_read_b128 v[242:245], v252 offset:36864
	ds_read_b128 v[184:187], v139 offset:20480
	s_waitcnt lgkmcnt(6)
	v_mfma_f32_32x32x16_bf16 v[96:111], v[196:199], v[148:151], v[96:111]
	s_waitcnt lgkmcnt(5)
	v_mfma_f32_32x32x16_bf16 v[80:95], v[238:241], v[148:151], v[80:95]
	s_waitcnt lgkmcnt(4)
	v_mfma_f32_32x32x16_bf16 v[112:127], v[196:199], v[180:183], v[112:127]
	v_mfma_f32_32x32x16_bf16 v[64:79], v[238:241], v[180:183], v[64:79]
	s_waitcnt lgkmcnt(2)
	v_mfma_f32_32x32x16_bf16 v[96:111], v[200:203], v[160:163], v[96:111]
	s_waitcnt lgkmcnt(1)
	v_mfma_f32_32x32x16_bf16 v[80:95], v[242:245], v[160:163], v[80:95]
	s_waitcnt lgkmcnt(0)
	v_mfma_f32_32x32x16_bf16 v[112:127], v[200:203], v[184:187], v[112:127]
	v_mfma_f32_32x32x16_bf16 v[64:79], v[242:245], v[184:187], v[64:79]
	s_setprio 0
	s_waitcnt vmcnt(2)
	s_barrier
	ds_read_b128 v[188:191], v232 offset:49152
	ds_read_b128 v[204:207], v232 offset:53248
	ds_read_b128 v[192:195], v233 offset:49152
	ds_read_b128 v[208:211], v233 offset:53248
	ds_read_b128 v[196:199], v237 offset:49152
	ds_read_b128 v[238:241], v237 offset:53248
	ds_read_b128 v[200:203], v252 offset:49152
	ds_read_b128 v[242:245], v252 offset:53248
	v_lshl_add_u64 v[246:247], v[132:133], 0, s[6:7]
	s_add_i32 m0, s32, 0x8000
	s_nop 0
	global_load_lds_dwordx4 v[246:247], off
	v_lshl_add_u64 v[248:249], v[134:135], 0, s[6:7]
	s_add_i32 m0, s32, 0x8400
	s_nop 0
	global_load_lds_dwordx4 v[248:249], off
	v_lshl_add_u64 v[246:247], v[132:133], 0, s[6:7]
	v_lshl_add_u64 v[246:247], v[246:247], 0, s[16:17]
	s_add_i32 m0, s32, 0x8800
	s_nop 0
	global_load_lds_dwordx4 v[246:247], off
	v_lshl_add_u64 v[248:249], v[134:135], 0, s[6:7]
	v_lshl_add_u64 v[248:249], v[248:249], 0, s[16:17]
	s_add_i32 m0, s32, 0x8c00
	s_nop 0
	global_load_lds_dwordx4 v[248:249], off
	v_lshl_add_u64 v[246:247], v[128:129], 0, s[6:7]
	v_lshl_add_u64 v[246:247], v[246:247], 0, s[14:15]
	s_add_i32 m0, s13, 0x2000
	s_nop 0
	global_load_lds_dwordx4 v[246:247], off
	v_lshl_add_u64 v[248:249], v[130:131], 0, s[6:7]
	v_lshl_add_u64 v[248:249], v[248:249], 0, s[14:15]
	s_add_i32 m0, s13, 0x2400
	s_nop 0
	global_load_lds_dwordx4 v[248:249], off
	s_add_u32 s4, s4, 0x80
	s_addc_u32 s5, s5, 0
	s_add_u32 s6, s6, 0x80
	s_addc_u32 s7, s7, 0
	s_setprio 1
	s_waitcnt lgkmcnt(7)
	v_mfma_f32_32x32x16_bf16 v[48:63], v[188:191], v[140:143], v[48:63]
	s_waitcnt lgkmcnt(6)
	v_mfma_f32_32x32x16_bf16 v[16:31], v[204:207], v[140:143], v[16:31]
	v_mfma_f32_32x32x16_bf16 v[32:47], v[188:191], v[164:167], v[32:47]
	v_mfma_f32_32x32x16_bf16 v[0:15], v[204:207], v[164:167], v[0:15]
	s_waitcnt lgkmcnt(5)
	v_mfma_f32_32x32x16_bf16 v[48:63], v[192:195], v[144:147], v[48:63]
	s_waitcnt lgkmcnt(4)
	v_mfma_f32_32x32x16_bf16 v[16:31], v[208:211], v[144:147], v[16:31]
	v_mfma_f32_32x32x16_bf16 v[32:47], v[192:195], v[170:173], v[32:47]
	v_mfma_f32_32x32x16_bf16 v[0:15], v[208:211], v[170:173], v[0:15]
	s_waitcnt lgkmcnt(3)
	v_mfma_f32_32x32x16_bf16 v[48:63], v[196:199], v[148:151], v[48:63]
	s_waitcnt lgkmcnt(2)
	v_mfma_f32_32x32x16_bf16 v[16:31], v[238:241], v[148:151], v[16:31]
	v_mfma_f32_32x32x16_bf16 v[32:47], v[196:199], v[180:183], v[32:47]
	v_mfma_f32_32x32x16_bf16 v[0:15], v[238:241], v[180:183], v[0:15]
	s_waitcnt lgkmcnt(1)
	v_mfma_f32_32x32x16_bf16 v[48:63], v[200:203], v[160:163], v[48:63]
	s_waitcnt lgkmcnt(0)
	v_mfma_f32_32x32x16_bf16 v[16:31], v[242:245], v[160:163], v[16:31]
	v_mfma_f32_32x32x16_bf16 v[32:47], v[200:203], v[184:187], v[32:47]
	v_mfma_f32_32x32x16_bf16 v[0:15], v[242:245], v[184:187], v[0:15]
	s_setprio 0
	s_add_i32 s37, s37, -1
	s_cmp_lg_u32 s37, 0
	s_cbranch_scc1 .Lk1_loop
	s_waitcnt vmcnt(0)
	s_barrier
	ds_read_b128 v[140:143], v136 offset:0
	ds_read_b128 v[188:191], v232 offset:32768
	ds_read_b128 v[204:207], v232 offset:36864
	ds_read_b128 v[164:167], v136 offset:4096
	ds_read_b128 v[144:147], v137 offset:0
	ds_read_b128 v[192:195], v233 offset:32768
	ds_read_b128 v[208:211], v233 offset:36864
	ds_read_b128 v[170:173], v137 offset:4096
	v_lshl_add_u64 v[246:247], v[132:133], 0, s[4:5]
	v_lshl_add_u64 v[246:247], v[246:247], 0, s[14:15]
	s_add_i32 m0, s32, 0xc000
	s_nop 0
	global_load_lds_dwordx4 v[246:247], off
	v_lshl_add_u64 v[248:249], v[134:135], 0, s[4:5]
	v_lshl_add_u64 v[248:249], v[248:249], 0, s[14:15]
	s_add_i32 m0, s32, 0xc400
	s_nop 0
	global_load_lds_dwordx4 v[248:249], off
	v_lshl_add_u64 v[246:247], v[132:133], 0, s[4:5]
	v_lshl_add_u64 v[246:247], v[246:247], 0, s[14:15]
	v_lshl_add_u64 v[246:247], v[246:247], 0, s[16:17]
	s_add_i32 m0, s32, 0xc800
	s_nop 0
	global_load_lds_dwordx4 v[246:247], off
	v_lshl_add_u64 v[248:249], v[134:135], 0, s[4:5]
	v_lshl_add_u64 v[248:249], v[248:249], 0, s[14:15]
	v_lshl_add_u64 v[248:249], v[248:249], 0, s[16:17]
	s_add_i32 m0, s32, 0xcc00
	s_nop 0
	global_load_lds_dwordx4 v[248:249], off
	v_lshl_add_u64 v[246:247], v[128:129], 0, s[6:7]
	s_add_i32 m0, s13, 0x4000
	s_nop 0
	global_load_lds_dwordx4 v[246:247], off
	v_lshl_add_u64 v[248:249], v[130:131], 0, s[6:7]
	s_add_i32 m0, s13, 0x4400
	s_nop 0
	global_load_lds_dwordx4 v[248:249], off
	s_setprio 1
	s_waitcnt lgkmcnt(6)
	v_mfma_f32_32x32x16_bf16 v[96:111], v[188:191], v[140:143], v[96:111]
	s_waitcnt lgkmcnt(5)
	v_mfma_f32_32x32x16_bf16 v[80:95], v[204:207], v[140:143], v[80:95]
	s_waitcnt lgkmcnt(4)
	v_mfma_f32_32x32x16_bf16 v[112:127], v[188:191], v[164:167], v[112:127]
	v_mfma_f32_32x32x16_bf16 v[64:79], v[204:207], v[164:167], v[64:79]
	ds_read_b128 v[148:151], v138 offset:0
	ds_read_b128 v[196:199], v237 offset:32768
	ds_read_b128 v[238:241], v237 offset:36864
	ds_read_b128 v[180:183], v138 offset:4096
	s_waitcnt lgkmcnt(6)
	v_mfma_f32_32x32x16_bf16 v[96:111], v[192:195], v[144:147], v[96:111]
	s_waitcnt lgkmcnt(5)
	v_mfma_f32_32x32x16_bf16 v[80:95], v[208:211], v[144:147], v[80:95]
	s_waitcnt lgkmcnt(4)
	v_mfma_f32_32x32x16_bf16 v[112:127], v[192:195], v[170:173], v[112:127]
	v_mfma_f32_32x32x16_bf16 v[64:79], v[208:211], v[170:173], v[64:79]
	ds_read_b128 v[160:163], v139 offset:0
	ds_read_b128 v[200:203], v252 offset:32768
	ds_read_b128 v[242:245], v252 offset:36864
	ds_read_b128 v[184:187], v139 offset:4096
	s_waitcnt lgkmcnt(6)
	v_mfma_f32_32x32x16_bf16 v[96:111], v[196:199], v[148:151], v[96:111]
	s_waitcnt lgkmcnt(5)
	v_mfma_f32_32x32x16_bf16 v[80:95], v[238:241], v[148:151], v[80:95]
	s_waitcnt lgkmcnt(4)
	v_mfma_f32_32x32x16_bf16 v[112:127], v[196:199], v[180:183], v[112:127]
	v_mfma_f32_32x32x16_bf16 v[64:79], v[238:241], v[180:183], v[64:79]
	s_waitcnt lgkmcnt(2)
	v_mfma_f32_32x32x16_bf16 v[96:111], v[200:203], v[160:163], v[96:111]
	s_waitcnt lgkmcnt(1)
	v_mfma_f32_32x32x16_bf16 v[80:95], v[242:245], v[160:163], v[80:95]
	s_waitcnt lgkmcnt(0)
	v_mfma_f32_32x32x16_bf16 v[112:127], v[200:203], v[184:187], v[112:127]
	v_mfma_f32_32x32x16_bf16 v[64:79], v[242:245], v[184:187], v[64:79]
	s_setprio 0
	s_waitcnt vmcnt(2)
	s_barrier
	ds_read_b128 v[188:191], v232 offset:49152
	ds_read_b128 v[204:207], v232 offset:53248
	ds_read_b128 v[192:195], v233 offset:49152
	ds_read_b128 v[208:211], v233 offset:53248
	ds_read_b128 v[196:199], v237 offset:49152
	ds_read_b128 v[238:241], v237 offset:53248
	ds_read_b128 v[200:203], v252 offset:49152
	ds_read_b128 v[242:245], v252 offset:53248
	v_lshl_add_u64 v[246:247], v[132:133], 0, s[6:7]
	s_add_i32 m0, s32, 0x8000
	s_nop 0
	global_load_lds_dwordx4 v[246:247], off
	v_lshl_add_u64 v[248:249], v[134:135], 0, s[6:7]
	s_add_i32 m0, s32, 0x8400
	s_nop 0
	global_load_lds_dwordx4 v[248:249], off
	v_lshl_add_u64 v[246:247], v[132:133], 0, s[6:7]
	v_lshl_add_u64 v[246:247], v[246:247], 0, s[16:17]
	s_add_i32 m0, s32, 0x8800
	s_nop 0
	global_load_lds_dwordx4 v[246:247], off
	v_lshl_add_u64 v[248:249], v[134:135], 0, s[6:7]
	v_lshl_add_u64 v[248:249], v[248:249], 0, s[16:17]
	s_add_i32 m0, s32, 0x8c00
	s_nop 0
	global_load_lds_dwordx4 v[248:249], off
	v_lshl_add_u64 v[246:247], v[128:129], 0, s[6:7]
	v_lshl_add_u64 v[246:247], v[246:247], 0, s[14:15]
	s_add_i32 m0, s13, 0x6000
	s_nop 0
	global_load_lds_dwordx4 v[246:247], off
	v_lshl_add_u64 v[248:249], v[130:131], 0, s[6:7]
	v_lshl_add_u64 v[248:249], v[248:249], 0, s[14:15]
	s_add_i32 m0, s13, 0x6400
	s_nop 0
	global_load_lds_dwordx4 v[248:249], off
	s_add_u32 s4, s4, 0x80
	s_addc_u32 s5, s5, 0
	s_add_u32 s6, s6, 0x80
	s_addc_u32 s7, s7, 0
	s_setprio 1
	s_waitcnt lgkmcnt(7)
	v_mfma_f32_32x32x16_bf16 v[48:63], v[188:191], v[140:143], v[48:63]
	s_waitcnt lgkmcnt(6)
	v_mfma_f32_32x32x16_bf16 v[16:31], v[204:207], v[140:143], v[16:31]
	v_mfma_f32_32x32x16_bf16 v[32:47], v[188:191], v[164:167], v[32:47]
	v_mfma_f32_32x32x16_bf16 v[0:15], v[204:207], v[164:167], v[0:15]
	s_waitcnt lgkmcnt(5)
	v_mfma_f32_32x32x16_bf16 v[48:63], v[192:195], v[144:147], v[48:63]
	s_waitcnt lgkmcnt(4)
	v_mfma_f32_32x32x16_bf16 v[16:31], v[208:211], v[144:147], v[16:31]
	v_mfma_f32_32x32x16_bf16 v[32:47], v[192:195], v[170:173], v[32:47]
	v_mfma_f32_32x32x16_bf16 v[0:15], v[208:211], v[170:173], v[0:15]
	s_waitcnt lgkmcnt(3)
	v_mfma_f32_32x32x16_bf16 v[48:63], v[196:199], v[148:151], v[48:63]
	s_waitcnt lgkmcnt(2)
	v_mfma_f32_32x32x16_bf16 v[16:31], v[238:241], v[148:151], v[16:31]
	v_mfma_f32_32x32x16_bf16 v[32:47], v[196:199], v[180:183], v[32:47]
	v_mfma_f32_32x32x16_bf16 v[0:15], v[238:241], v[180:183], v[0:15]
	s_waitcnt lgkmcnt(1)
	v_mfma_f32_32x32x16_bf16 v[48:63], v[200:203], v[160:163], v[48:63]
	s_waitcnt lgkmcnt(0)
	v_mfma_f32_32x32x16_bf16 v[16:31], v[242:245], v[160:163], v[16:31]
	v_mfma_f32_32x32x16_bf16 v[32:47], v[200:203], v[184:187], v[32:47]
	v_mfma_f32_32x32x16_bf16 v[0:15], v[242:245], v[184:187], v[0:15]
	s_setprio 0
	s_waitcnt vmcnt(0)
	s_barrier
	ds_read_b128 v[140:143], v136 offset:16384
	ds_read_b128 v[188:191], v232 offset:32768
	ds_read_b128 v[204:207], v232 offset:36864
	ds_read_b128 v[164:167], v136 offset:20480
	ds_read_b128 v[144:147], v137 offset:16384
	ds_read_b128 v[192:195], v233 offset:32768
	ds_read_b128 v[208:211], v233 offset:36864
	ds_read_b128 v[170:173], v137 offset:20480
	v_lshl_add_u64 v[246:247], v[132:133], 0, s[4:5]
	v_lshl_add_u64 v[246:247], v[246:247], 0, s[14:15]
	s_add_i32 m0, s32, 0xc000
	s_nop 0
	global_load_lds_dwordx4 v[246:247], off
	v_lshl_add_u64 v[248:249], v[134:135], 0, s[4:5]
	v_lshl_add_u64 v[248:249], v[248:249], 0, s[14:15]
	s_add_i32 m0, s32, 0xc400
	s_nop 0
	global_load_lds_dwordx4 v[248:249], off
	v_lshl_add_u64 v[246:247], v[132:133], 0, s[4:5]
	v_lshl_add_u64 v[246:247], v[246:247], 0, s[14:15]
	v_lshl_add_u64 v[246:247], v[246:247], 0, s[16:17]
	s_add_i32 m0, s32, 0xc800
	s_nop 0
	global_load_lds_dwordx4 v[246:247], off
	v_lshl_add_u64 v[248:249], v[134:135], 0, s[4:5]
	v_lshl_add_u64 v[248:249], v[248:249], 0, s[14:15]
	v_lshl_add_u64 v[248:249], v[248:249], 0, s[16:17]
	s_add_i32 m0, s32, 0xcc00
	s_nop 0
	global_load_lds_dwordx4 v[248:249], off
	s_setprio 1
	s_waitcnt lgkmcnt(6)
	v_mfma_f32_32x32x16_bf16 v[96:111], v[188:191], v[140:143], v[96:111]
	s_waitcnt lgkmcnt(5)
	v_mfma_f32_32x32x16_bf16 v[80:95], v[204:207], v[140:143], v[80:95]
	s_waitcnt lgkmcnt(4)
	v_mfma_f32_32x32x16_bf16 v[112:127], v[188:191], v[164:167], v[112:127]
	v_mfma_f32_32x32x16_bf16 v[64:79], v[204:207], v[164:167], v[64:79]
	ds_read_b128 v[148:151], v138 offset:16384
	ds_read_b128 v[196:199], v237 offset:32768
	ds_read_b128 v[238:241], v237 offset:36864
	ds_read_b128 v[180:183], v138 offset:20480
	s_waitcnt lgkmcnt(6)
	v_mfma_f32_32x32x16_bf16 v[96:111], v[192:195], v[144:147], v[96:111]
	s_waitcnt lgkmcnt(5)
	v_mfma_f32_32x32x16_bf16 v[80:95], v[208:211], v[144:147], v[80:95]
	s_waitcnt lgkmcnt(4)
	v_mfma_f32_32x32x16_bf16 v[112:127], v[192:195], v[170:173], v[112:127]
	v_mfma_f32_32x32x16_bf16 v[64:79], v[208:211], v[170:173], v[64:79]
	ds_read_b128 v[160:163], v139 offset:16384
	ds_read_b128 v[200:203], v252 offset:32768
	ds_read_b128 v[242:245], v252 offset:36864
	ds_read_b128 v[184:187], v139 offset:20480
	s_waitcnt lgkmcnt(6)
	v_mfma_f32_32x32x16_bf16 v[96:111], v[196:199], v[148:151], v[96:111]
	s_waitcnt lgkmcnt(5)
	v_mfma_f32_32x32x16_bf16 v[80:95], v[238:241], v[148:151], v[80:95]
	s_waitcnt lgkmcnt(4)
	v_mfma_f32_32x32x16_bf16 v[112:127], v[196:199], v[180:183], v[112:127]
	v_mfma_f32_32x32x16_bf16 v[64:79], v[238:241], v[180:183], v[64:79]
	s_waitcnt lgkmcnt(2)
	v_mfma_f32_32x32x16_bf16 v[96:111], v[200:203], v[160:163], v[96:111]
	s_waitcnt lgkmcnt(1)
	v_mfma_f32_32x32x16_bf16 v[80:95], v[242:245], v[160:163], v[80:95]
	s_waitcnt lgkmcnt(0)
	v_mfma_f32_32x32x16_bf16 v[112:127], v[200:203], v[184:187], v[112:127]
	v_mfma_f32_32x32x16_bf16 v[64:79], v[242:245], v[184:187], v[64:79]
	s_setprio 0
	s_waitcnt vmcnt(0)
	s_barrier
	ds_read_b128 v[188:191], v232 offset:49152
	ds_read_b128 v[204:207], v232 offset:53248
	ds_read_b128 v[192:195], v233 offset:49152
	ds_read_b128 v[208:211], v233 offset:53248
	ds_read_b128 v[196:199], v237 offset:49152
	ds_read_b128 v[238:241], v237 offset:53248
	ds_read_b128 v[200:203], v252 offset:49152
	ds_read_b128 v[242:245], v252 offset:53248
	s_setprio 1
	s_waitcnt lgkmcnt(7)
	v_mfma_f32_32x32x16_bf16 v[48:63], v[188:191], v[140:143], v[48:63]
	s_waitcnt lgkmcnt(6)
	v_mfma_f32_32x32x16_bf16 v[16:31], v[204:207], v[140:143], v[16:31]
	v_mfma_f32_32x32x16_bf16 v[32:47], v[188:191], v[164:167], v[32:47]
	v_mfma_f32_32x32x16_bf16 v[0:15], v[204:207], v[164:167], v[0:15]
	s_waitcnt lgkmcnt(5)
	v_mfma_f32_32x32x16_bf16 v[48:63], v[192:195], v[144:147], v[48:63]
	s_waitcnt lgkmcnt(4)
	v_mfma_f32_32x32x16_bf16 v[16:31], v[208:211], v[144:147], v[16:31]
	v_mfma_f32_32x32x16_bf16 v[32:47], v[192:195], v[170:173], v[32:47]
	v_mfma_f32_32x32x16_bf16 v[0:15], v[208:211], v[170:173], v[0:15]
	s_waitcnt lgkmcnt(3)
	v_mfma_f32_32x32x16_bf16 v[48:63], v[196:199], v[148:151], v[48:63]
	s_waitcnt lgkmcnt(2)
	v_mfma_f32_32x32x16_bf16 v[16:31], v[238:241], v[148:151], v[16:31]
	v_mfma_f32_32x32x16_bf16 v[32:47], v[196:199], v[180:183], v[32:47]
	v_mfma_f32_32x32x16_bf16 v[0:15], v[238:241], v[180:183], v[0:15]
	s_waitcnt lgkmcnt(1)
	v_mfma_f32_32x32x16_bf16 v[48:63], v[200:203], v[160:163], v[48:63]
	s_waitcnt lgkmcnt(0)
	v_mfma_f32_32x32x16_bf16 v[16:31], v[242:245], v[160:163], v[16:31]
	v_mfma_f32_32x32x16_bf16 v[32:47], v[200:203], v[184:187], v[32:47]
	v_mfma_f32_32x32x16_bf16 v[0:15], v[242:245], v[184:187], v[0:15]
	s_setprio 0

.LBB0_748:
	s_lshr_b32 s5, s10, 2
	s_and_b32 s5, s5, 56
	s_and_b32 s4, s9, 7
	s_add_i32 s5, s5, s89
	s_add_i32 s4, s5, s4
	v_mov_b32_e32 v152, v179
	s_lshl_b32 s11, s4, 7
	s_bfe_u32 s4, s8, 0x20008
	s_mul_i32 s6, s4, 0x160000
	v_readfirstlane_b32 s24, v152
	s_and_b32 s4, s10, 7
	s_ashr_i32 s17, s24, 6
	v_and_b32_e32 v1, 60, v152
	s_or_b32 s4, s5, s4
	s_lshl_b32 s5, s10, 5
	v_lshl_or_b32 v1, s17, 7, v1
	s_and_b32 s7, s5, 0x300
	v_bfe_u32 v13, v152, 2, 4
	s_and_b32 s5, s24, 0xffffc0
	v_ashrrev_i32_e32 v17, 2, v1
	v_or_b32_e32 v2, s5, v13
	s_lshl_b32 s5, s17, 11
	v_lshl_add_u32 v1, s4, 7, v17
	s_waitcnt vmcnt(0)
	v_mov_b64_e32 v[8:9], s[78:79]
	v_lshrrev_b32_e32 v12, 4, v152
	s_add_i32 s15, s5, 16
	v_mad_i64_i32 v[10:11], s[4:5], v1, s45, v[8:9]
	v_or_b32_e32 v1, 16, v1
	v_xor_b32_e32 v0, v12, v152
	v_mad_i64_i32 v[8:9], s[4:5], v1, s45, v[8:9]
	s_lshr_b32 s13, s8, 8
	s_and_b32 s12, s17, 1
	s_ashr_i32 s14, s24, 7
	v_lshlrev_b32_e32 v0, 3, v0
	s_add_i32 s16, s15, 0x400
	s_mulk_i32 s7, 0x1600
	v_readlane_b32 s4, v254, 1
	v_and_b32_e32 v14, 24, v0
	s_add_u32 s4, s4, s7
	v_readlane_b32 s5, v254, 2
	v_mul_u32_u24_e32 v0, 0xb00, v2
	v_lshlrev_b32_e32 v176, 1, v14
	s_addc_u32 s5, s5, 0
	s_lshl_b32 s7, s17, 12
	v_or_b32_e32 v0, v0, v14
	v_lshl_add_u64 v[10:11], v[10:11], 0, v[176:177]
	s_mov_b32 m0, s15
	s_add_i32 s17, s7, 16
	v_bfe_u32 v154, v152, 5, 1
	v_add_u32_e32 v2, 0xb000, v0
	v_lshrrev_b32_e32 v3, 2, v152
	v_lshl_add_u64 v[8:9], v[8:9], 0, v[176:177]
	s_mov_b32 m0, s16
	s_add_i32 s18, s17, 0x2000
	v_ashrrev_i32_e32 v1, 31, v0
	v_add_u32_e32 v4, 0x16000, v0
	v_add_u32_e32 v6, 0x21000, v0
	v_bfe_u32 v5, v152, 2, 2
	v_bitop3_b32 v15, v154, v3, 3 bitop3:0x78
	v_lshl_add_u64 v[0:1], v[0:1], 1, s[4:5]
	s_mov_b32 m0, s18
	v_ashrrev_i32_e32 v3, 31, v2
	s_add_i32 s19, s17, 0x2400
	v_bitop3_b32 v16, v154, v5, 2 bitop3:0x36
	v_lshl_add_u64 v[0:1], v[2:3], 1, s[4:5]
	s_mov_b32 m0, s19
	v_ashrrev_i32_e32 v5, 31, v4
	s_add_i32 s20, s17, 0x2800
	v_lshl_add_u64 v[0:1], v[4:5], 1, s[4:5]
	s_mov_b32 m0, s20
	v_ashrrev_i32_e32 v7, 31, v6
	s_add_i32 s21, s17, 0x2c00
	v_lshl_add_u64 v[0:1], v[6:7], 1, s[4:5]
	s_mov_b32 m0, s21
	s_lshl_b32 s4, s12, 13
	v_lshl_add_u32 v0, v15, 4, 16
	s_lshl_b32 s5, s14, 12
	v_add_u32_e32 v3, s5, v0
	v_add_u32_e32 v4, s4, v0
	v_lshl_add_u32 v0, v16, 4, 16
	v_add_u32_e32 v7, s11, v17
	v_bitop3_b32 v8, v12, 3, v152 bitop3:0x48
	v_add_u32_e32 v5, s5, v0
	v_add_u32_e32 v6, s4, v0
	v_mad_i64_i32 v[0:1], s[4:5], v7, s45, 0
	v_lshlrev_b32_e32 v8, 4, v8
	v_or_b32_e32 v0, v0, v8
	v_lshl_add_u64 v[128:129], s[78:79], 0, v[0:1]
	v_or_b32_e32 v0, 16, v7
	v_mad_i64_i32 v[0:1], s[4:5], v0, s45, 0
	s_lshr_b32 s4, s24, 6
	v_or_b32_e32 v0, v0, v8
	s_mul_i32 s7, s4, 0x2c000
	v_lshl_add_u64 v[130:131], s[78:79], 0, v[0:1]
	v_mov_b32_e32 v0, s7
	v_mad_u32_u24 v0, v13, s25, v0
	v_or_b32_e32 v0, v0, v14
	s_add_u32 s4, s80, s6
	v_ashrrev_i32_e32 v1, 31, v0
	s_addc_u32 s5, s81, 0
	s_add_i32 s6, s7, 0xb000
	v_lshl_add_u64 v[132:133], v[0:1], 1, s[4:5]
	v_mov_b32_e32 v0, s6
	v_mad_u32_u24 v0, v13, s25, v0
	v_or_b32_e32 v0, v0, v14
	v_ashrrev_i32_e32 v1, 31, v0
	s_add_i32 s6, s7, 0x16000
	v_lshl_add_u64 v[134:135], v[0:1], 1, s[4:5]
	v_mov_b32_e32 v0, s6
	v_mad_u32_u24 v0, v13, s25, v0
	v_or_b32_e32 v0, v0, v14
	v_ashrrev_i32_e32 v1, 31, v0
	s_add_i32 s6, s7, 0x21000
	v_lshl_add_u64 v[136:137], v[0:1], 1, s[4:5]
	v_mov_b32_e32 v0, s6
	v_mad_u32_u24 v0, v13, s25, v0
	v_and_b32_e32 v153, 31, v152
	v_or_b32_e32 v0, v0, v14
	v_lshlrev_b32_e32 v2, 6, v153
	v_ashrrev_i32_e32 v1, 31, v0
	v_mov_b32_e32 v64, 0
	v_lshl_add_u64 v[138:139], v[0:1], 1, s[4:5]
	s_mov_b32 s24, 0
	s_mov_b64 s[4:5], 0
	v_add_u32_e32 v155, v3, v2
	v_add_u32_e32 v156, v4, v2
	v_add_u32_e32 v157, v5, v2
	v_add_u32_e32 v158, v6, v2
	v_mov_b32_e32 v65, v64
	v_mov_b32_e32 v66, v64
	v_mov_b32_e32 v67, v64
	v_mov_b32_e32 v68, v64
	v_mov_b32_e32 v69, v64
	v_mov_b32_e32 v70, v64
	v_mov_b32_e32 v71, v64
	v_mov_b32_e32 v72, v64
	v_mov_b32_e32 v73, v64
	v_mov_b32_e32 v74, v64
	v_mov_b32_e32 v75, v64
	v_mov_b32_e32 v76, v64
	v_mov_b32_e32 v77, v64
	v_mov_b32_e32 v78, v64
	v_mov_b32_e32 v79, v64
	v_mov_b32_e32 v80, v64
	v_mov_b32_e32 v81, v64
	v_mov_b32_e32 v82, v64
	v_mov_b32_e32 v83, v64
	v_mov_b32_e32 v84, v64
	v_mov_b32_e32 v85, v64
	v_mov_b32_e32 v86, v64
	v_mov_b32_e32 v87, v64
	v_mov_b32_e32 v88, v64
	v_mov_b32_e32 v89, v64
	v_mov_b32_e32 v90, v64
	v_mov_b32_e32 v91, v64
	v_mov_b32_e32 v92, v64
	v_mov_b32_e32 v93, v64
	v_mov_b32_e32 v94, v64
	v_mov_b32_e32 v95, v64
	v_mov_b32_e32 v16, v64
	v_mov_b32_e32 v17, v64
	v_mov_b32_e32 v18, v64
	v_mov_b32_e32 v19, v64
	v_mov_b32_e32 v20, v64
	v_mov_b32_e32 v21, v64
	v_mov_b32_e32 v22, v64
	v_mov_b32_e32 v23, v64
	v_mov_b32_e32 v24, v64
	v_mov_b32_e32 v25, v64
	v_mov_b32_e32 v26, v64
	v_mov_b32_e32 v27, v64
	v_mov_b32_e32 v28, v64
	v_mov_b32_e32 v29, v64
	v_mov_b32_e32 v30, v64
	v_mov_b32_e32 v31, v64
	v_mov_b32_e32 v0, v64
	v_mov_b32_e32 v1, v64
	v_mov_b32_e32 v2, v64
	v_mov_b32_e32 v3, v64
	v_mov_b32_e32 v4, v64
	v_mov_b32_e32 v5, v64
	v_mov_b32_e32 v6, v64
	v_mov_b32_e32 v7, v64
	v_mov_b32_e32 v8, v64
	v_mov_b32_e32 v9, v64
	v_mov_b32_e32 v10, v64
	v_mov_b32_e32 v11, v64
	v_mov_b32_e32 v12, v64
	v_mov_b32_e32 v13, v64
	v_mov_b32_e32 v14, v64
	v_mov_b32_e32 v15, v64
	v_mov_b32_e32 v112, v64
	v_mov_b32_e32 v113, v64
	v_mov_b32_e32 v114, v64
	v_mov_b32_e32 v115, v64
	v_mov_b32_e32 v116, v64
	v_mov_b32_e32 v117, v64
	v_mov_b32_e32 v118, v64
	v_mov_b32_e32 v119, v64
	v_mov_b32_e32 v120, v64
	v_mov_b32_e32 v121, v64
	v_mov_b32_e32 v122, v64
	v_mov_b32_e32 v123, v64
	v_mov_b32_e32 v124, v64
	v_mov_b32_e32 v125, v64
	v_mov_b32_e32 v126, v64
	v_mov_b32_e32 v127, v64
	v_mov_b32_e32 v96, v64
	v_mov_b32_e32 v97, v64
	v_mov_b32_e32 v98, v64
	v_mov_b32_e32 v99, v64
	v_mov_b32_e32 v100, v64
	v_mov_b32_e32 v101, v64
	v_mov_b32_e32 v102, v64
	v_mov_b32_e32 v103, v64
	v_mov_b32_e32 v104, v64
	v_mov_b32_e32 v105, v64
	v_mov_b32_e32 v106, v64
	v_mov_b32_e32 v107, v64
	v_mov_b32_e32 v108, v64
	v_mov_b32_e32 v109, v64
	v_mov_b32_e32 v110, v64
	v_mov_b32_e32 v111, v64
	v_mov_b32_e32 v48, v64
	v_mov_b32_e32 v49, v64
	v_mov_b32_e32 v50, v64
	v_mov_b32_e32 v51, v64
	v_mov_b32_e32 v52, v64
	v_mov_b32_e32 v53, v64
	v_mov_b32_e32 v54, v64
	v_mov_b32_e32 v55, v64
	v_mov_b32_e32 v56, v64
	v_mov_b32_e32 v57, v64
	v_mov_b32_e32 v58, v64
	v_mov_b32_e32 v59, v64
	v_mov_b32_e32 v60, v64
	v_mov_b32_e32 v61, v64
	v_mov_b32_e32 v62, v64
	v_mov_b32_e32 v63, v64
	v_mov_b32_e32 v32, v64
	v_mov_b32_e32 v33, v64
	v_mov_b32_e32 v34, v64
	v_mov_b32_e32 v35, v64
	v_mov_b32_e32 v36, v64
	v_mov_b32_e32 v37, v64
	v_mov_b32_e32 v38, v64
	v_mov_b32_e32 v39, v64
	v_mov_b32_e32 v40, v64
	v_mov_b32_e32 v41, v64
	v_mov_b32_e32 v42, v64
	v_mov_b32_e32 v43, v64
	v_mov_b32_e32 v44, v64
	v_mov_b32_e32 v45, v64
	v_mov_b32_e32 v46, v64
	v_mov_b32_e32 v47, v64
	v_readfirstlane_b32 s62, v179
	v_readfirstlane_b32 s56, v128
	v_readfirstlane_b32 s57, v129
	v_readfirstlane_b32 s58, v132
	v_readfirstlane_b32 s59, v133
	s_lshr_b32 s62, s62, 6
	s_mul_i32 s7, s62, 0x16000
	s_sub_u32 s56, s56, s7
	s_subb_u32 s57, s57, 0
	s_and_b32 s7, s62, 1
	s_mul_i32 s7, s7, 0x2c000
	s_sub_u32 s58, s58, s7
	s_subb_u32 s59, s59, 0
	s_add_u32 s58, s58, 0x8300000
	s_addc_u32 s59, s59, 0
	s_mov_b32 s6, 0x1600
	v_and_b32_e32 v140, 63, v179
	v_lshrrev_b32_e32 v141, 3, v140
	v_lshrrev_b32_e32 v143, 4, v140
	v_and_b32_e32 v142, 7, v140
	v_xor_b32_e32 v142, v142, v143
	v_lshlrev_b32_e32 v142, 4, v142
	v_mad_u32_u24 v176, v141, s6, v142
	v_lshl_add_u64 v[128:129], s[56:57], 0, v[176:177]
	v_lshl_add_u64 v[132:133], s[58:59], 0, v[176:177]
	v_xor_b32_e32 v142, 64, v142
	v_mad_u32_u24 v176, v141, s6, v142
	s_add_u32 s60, s56, 0xb000
	s_addc_u32 s61, s57, 0
	v_lshl_add_u64 v[130:131], s[60:61], 0, v[176:177]
	s_add_u32 s60, s58, 0xb000
	s_addc_u32 s61, s59, 0
	s_nop 0
	v_lshl_add_u64 v[134:135], s[60:61], 0, v[176:177]
	v_and_b32_e32 v144, 31, v179
	v_bfe_u32 v145, v179, 5, 1
	v_bfe_u32 v143, v179, 1, 3
	v_xor_b32_e32 v145, v145, v143
	s_lshr_b32 s7, s62, 1
	s_lshl_b32 s7, s7, 13
	s_add_i32 s7, s7, 16
	v_lshl_add_u32 v146, v144, 7, s7
	s_and_b32 s7, s62, 1
	s_lshl_b32 s7, s7, 13
	s_add_i32 s7, s7, 16
	v_lshl_add_u32 v147, v144, 7, s7
	v_xor_b32_e32 v143, 0, v145
	v_lshl_add_u32 v136, v143, 4, v146
	v_lshl_add_u32 v232, v143, 4, v147
	v_xor_b32_e32 v143, 2, v145
	v_lshl_add_u32 v137, v143, 4, v146
	v_lshl_add_u32 v233, v143, 4, v147
	v_xor_b32_e32 v143, 4, v145
	v_lshl_add_u32 v138, v143, 4, v146
	v_lshl_add_u32 v237, v143, 4, v147
	v_xor_b32_e32 v143, 6, v145
	v_lshl_add_u32 v139, v143, 4, v146
	v_lshl_add_u32 v252, v143, 4, v147
	s_lshl_b32 s63, s62, 11
	s_add_i32 s63, s63, 16
	s_lshl_b32 s4, s62, 12
	s_add_i32 s4, s4, 16
	s_mov_b64 s[48:49], 0
	s_mov_b64 s[50:51], 0x80
	s_mov_b32 s52, 0x58000
	s_mov_b32 s53, 0
	s_mov_b32 s54, 0x16000
	s_mov_b32 s55, 0
	s_add_i32 m0, s63, 0x0
	s_nop 0
	global_load_lds_dwordx4 v[128:129], off
	s_add_i32 m0, s63, 0x400
	s_nop 0
	global_load_lds_dwordx4 v[130:131], off
	v_lshl_add_u64 v[246:247], v[128:129], 0, s[52:53]
	s_add_i32 m0, s63, 0x2000
	s_nop 0
	global_load_lds_dwordx4 v[246:247], off
	v_lshl_add_u64 v[248:249], v[130:131], 0, s[52:53]
	s_add_i32 m0, s63, 0x2400
	s_nop 0
	global_load_lds_dwordx4 v[248:249], off
	s_add_i32 m0, s4, 0x8000
	s_nop 0
	global_load_lds_dwordx4 v[132:133], off
	s_add_i32 m0, s4, 0x8400
	s_nop 0
	global_load_lds_dwordx4 v[134:135], off
	v_lshl_add_u64 v[246:247], v[132:133], 0, s[54:55]
	s_add_i32 m0, s4, 0x8800
	s_nop 0
	global_load_lds_dwordx4 v[246:247], off
	v_lshl_add_u64 v[248:249], v[134:135], 0, s[54:55]
	s_add_i32 m0, s4, 0x8c00
	s_nop 0
	global_load_lds_dwordx4 v[248:249], off
	s_movk_i32 s5, 21
.Lk4_loop:
	s_waitcnt vmcnt(0)
	s_barrier
	ds_read_b128 v[140:143], v136 offset:0
	ds_read_b128 v[188:191], v232 offset:32768
	ds_read_b128 v[204:207], v232 offset:36864
	ds_read_b128 v[164:167], v136 offset:4096
	ds_read_b128 v[144:147], v137 offset:0
	ds_read_b128 v[192:195], v233 offset:32768
	ds_read_b128 v[208:211], v233 offset:36864
	ds_read_b128 v[170:173], v137 offset:4096
	v_lshl_add_u64 v[246:247], v[132:133], 0, s[48:49]
	v_lshl_add_u64 v[246:247], v[246:247], 0, s[52:53]
	s_add_i32 m0, s4, 0xc000
	s_nop 0
	global_load_lds_dwordx4 v[246:247], off
	v_lshl_add_u64 v[248:249], v[134:135], 0, s[48:49]
	v_lshl_add_u64 v[248:249], v[248:249], 0, s[52:53]
	s_add_i32 m0, s4, 0xc400
	s_nop 0
	global_load_lds_dwordx4 v[248:249], off
	v_lshl_add_u64 v[246:247], v[132:133], 0, s[48:49]
	v_lshl_add_u64 v[246:247], v[246:247], 0, s[52:53]
	v_lshl_add_u64 v[246:247], v[246:247], 0, s[54:55]
	s_add_i32 m0, s4, 0xc800
	s_nop 0
	global_load_lds_dwordx4 v[246:247], off
	v_lshl_add_u64 v[248:249], v[134:135], 0, s[48:49]
	v_lshl_add_u64 v[248:249], v[248:249], 0, s[52:53]
	v_lshl_add_u64 v[248:249], v[248:249], 0, s[54:55]
	s_add_i32 m0, s4, 0xcc00
	s_nop 0
	global_load_lds_dwordx4 v[248:249], off
	v_lshl_add_u64 v[246:247], v[128:129], 0, s[50:51]
	s_add_i32 m0, s63, 0x4000
	s_nop 0
	global_load_lds_dwordx4 v[246:247], off
	v_lshl_add_u64 v[248:249], v[130:131], 0, s[50:51]
	s_add_i32 m0, s63, 0x4400
	s_nop 0
	global_load_lds_dwordx4 v[248:249], off
	s_setprio 1
	s_waitcnt lgkmcnt(6)
	v_mfma_f32_32x32x16_bf16 v[64:79], v[188:191], v[140:143], v[64:79]
	s_waitcnt lgkmcnt(5)
	v_mfma_f32_32x32x16_bf16 v[80:95], v[204:207], v[140:143], v[80:95]
	s_waitcnt lgkmcnt(4)
	v_mfma_f32_32x32x16_bf16 v[112:127], v[188:191], v[164:167], v[112:127]
	v_mfma_f32_32x32x16_bf16 v[96:111], v[204:207], v[164:167], v[96:111]
	ds_read_b128 v[148:151], v138 offset:0
	ds_read_b128 v[196:199], v237 offset:32768
	ds_read_b128 v[238:241], v237 offset:36864
	ds_read_b128 v[180:183], v138 offset:4096
	s_waitcnt lgkmcnt(6)
	v_mfma_f32_32x32x16_bf16 v[64:79], v[192:195], v[144:147], v[64:79]
	s_waitcnt lgkmcnt(5)
	v_mfma_f32_32x32x16_bf16 v[80:95], v[208:211], v[144:147], v[80:95]
	s_waitcnt lgkmcnt(4)
	v_mfma_f32_32x32x16_bf16 v[112:127], v[192:195], v[170:173], v[112:127]
	v_mfma_f32_32x32x16_bf16 v[96:111], v[208:211], v[170:173], v[96:111]
	ds_read_b128 v[160:163], v139 offset:0
	ds_read_b128 v[200:203], v252 offset:32768
	ds_read_b128 v[242:245], v252 offset:36864
	ds_read_b128 v[184:187], v139 offset:4096
	s_waitcnt lgkmcnt(6)
	v_mfma_f32_32x32x16_bf16 v[64:79], v[196:199], v[148:151], v[64:79]
	s_waitcnt lgkmcnt(5)
	v_mfma_f32_32x32x16_bf16 v[80:95], v[238:241], v[148:151], v[80:95]
	s_waitcnt lgkmcnt(4)
	v_mfma_f32_32x32x16_bf16 v[112:127], v[196:199], v[180:183], v[112:127]
	v_mfma_f32_32x32x16_bf16 v[96:111], v[238:241], v[180:183], v[96:111]
	s_waitcnt lgkmcnt(2)
	v_mfma_f32_32x32x16_bf16 v[64:79], v[200:203], v[160:163], v[64:79]
	s_waitcnt lgkmcnt(1)
	v_mfma_f32_32x32x16_bf16 v[80:95], v[242:245], v[160:163], v[80:95]
	s_waitcnt lgkmcnt(0)
	v_mfma_f32_32x32x16_bf16 v[112:127], v[200:203], v[184:187], v[112:127]
	v_mfma_f32_32x32x16_bf16 v[96:111], v[242:245], v[184:187], v[96:111]
	s_setprio 0
	s_waitcnt vmcnt(2)
	s_barrier
	ds_read_b128 v[188:191], v232 offset:49152
	ds_read_b128 v[204:207], v232 offset:53248
	ds_read_b128 v[192:195], v233 offset:49152
	ds_read_b128 v[208:211], v233 offset:53248
	ds_read_b128 v[196:199], v237 offset:49152
	ds_read_b128 v[238:241], v237 offset:53248
	ds_read_b128 v[200:203], v252 offset:49152
	ds_read_b128 v[242:245], v252 offset:53248
	v_lshl_add_u64 v[246:247], v[132:133], 0, s[50:51]
	s_add_i32 m0, s4, 0x8000
	s_nop 0
	global_load_lds_dwordx4 v[246:247], off
	v_lshl_add_u64 v[248:249], v[134:135], 0, s[50:51]
	s_add_i32 m0, s4, 0x8400
	s_nop 0
	global_load_lds_dwordx4 v[248:249], off
	v_lshl_add_u64 v[246:247], v[132:133], 0, s[50:51]
	v_lshl_add_u64 v[246:247], v[246:247], 0, s[54:55]
	s_add_i32 m0, s4, 0x8800
	s_nop 0
	global_load_lds_dwordx4 v[246:247], off
	v_lshl_add_u64 v[248:249], v[134:135], 0, s[50:51]
	v_lshl_add_u64 v[248:249], v[248:249], 0, s[54:55]
	s_add_i32 m0, s4, 0x8c00
	s_nop 0
	global_load_lds_dwordx4 v[248:249], off
	v_lshl_add_u64 v[246:247], v[128:129], 0, s[50:51]
	v_lshl_add_u64 v[246:247], v[246:247], 0, s[52:53]
	s_add_i32 m0, s63, 0x6000
	s_nop 0
	global_load_lds_dwordx4 v[246:247], off
	v_lshl_add_u64 v[248:249], v[130:131], 0, s[50:51]
	v_lshl_add_u64 v[248:249], v[248:249], 0, s[52:53]
	s_add_i32 m0, s63, 0x6400
	s_nop 0
	global_load_lds_dwordx4 v[248:249], off
	s_add_u32 s48, s48, 0x80
	s_addc_u32 s49, s49, 0
	s_add_u32 s50, s50, 0x80
	s_addc_u32 s51, s51, 0
	s_setprio 1
	s_waitcnt lgkmcnt(7)
	v_mfma_f32_32x32x16_bf16 v[16:31], v[188:191], v[140:143], v[16:31]
	s_waitcnt lgkmcnt(6)
	v_mfma_f32_32x32x16_bf16 v[0:15], v[204:207], v[140:143], v[0:15]
	v_mfma_f32_32x32x16_bf16 v[48:63], v[188:191], v[164:167], v[48:63]
	v_mfma_f32_32x32x16_bf16 v[32:47], v[204:207], v[164:167], v[32:47]
	s_waitcnt lgkmcnt(5)
	v_mfma_f32_32x32x16_bf16 v[16:31], v[192:195], v[144:147], v[16:31]
	s_waitcnt lgkmcnt(4)
	v_mfma_f32_32x32x16_bf16 v[0:15], v[208:211], v[144:147], v[0:15]
	v_mfma_f32_32x32x16_bf16 v[48:63], v[192:195], v[170:173], v[48:63]
	v_mfma_f32_32x32x16_bf16 v[32:47], v[208:211], v[170:173], v[32:47]
	s_waitcnt lgkmcnt(3)
	v_mfma_f32_32x32x16_bf16 v[16:31], v[196:199], v[148:151], v[16:31]
	s_waitcnt lgkmcnt(2)
	v_mfma_f32_32x32x16_bf16 v[0:15], v[238:241], v[148:151], v[0:15]
	v_mfma_f32_32x32x16_bf16 v[48:63], v[196:199], v[180:183], v[48:63]
	v_mfma_f32_32x32x16_bf16 v[32:47], v[238:241], v[180:183], v[32:47]
	s_waitcnt lgkmcnt(1)
	v_mfma_f32_32x32x16_bf16 v[16:31], v[200:203], v[160:163], v[16:31]
	s_waitcnt lgkmcnt(0)
	v_mfma_f32_32x32x16_bf16 v[0:15], v[242:245], v[160:163], v[0:15]
	v_mfma_f32_32x32x16_bf16 v[48:63], v[200:203], v[184:187], v[48:63]
	v_mfma_f32_32x32x16_bf16 v[32:47], v[242:245], v[184:187], v[32:47]
	s_setprio 0
	s_waitcnt vmcnt(0)
	s_barrier
	ds_read_b128 v[140:143], v136 offset:16384
	ds_read_b128 v[188:191], v232 offset:32768
	ds_read_b128 v[204:207], v232 offset:36864
	ds_read_b128 v[164:167], v136 offset:20480
	ds_read_b128 v[144:147], v137 offset:16384
	ds_read_b128 v[192:195], v233 offset:32768
	ds_read_b128 v[208:211], v233 offset:36864
	ds_read_b128 v[170:173], v137 offset:20480
	v_lshl_add_u64 v[246:247], v[132:133], 0, s[48:49]
	v_lshl_add_u64 v[246:247], v[246:247], 0, s[52:53]
	s_add_i32 m0, s4, 0xc000
	s_nop 0
	global_load_lds_dwordx4 v[246:247], off
	v_lshl_add_u64 v[248:249], v[134:135], 0, s[48:49]
	v_lshl_add_u64 v[248:249], v[248:249], 0, s[52:53]
	s_add_i32 m0, s4, 0xc400
	s_nop 0
	global_load_lds_dwordx4 v[248:249], off
	v_lshl_add_u64 v[246:247], v[132:133], 0, s[48:49]
	v_lshl_add_u64 v[246:247], v[246:247], 0, s[52:53]
	v_lshl_add_u64 v[246:247], v[246:247], 0, s[54:55]
	s_add_i32 m0, s4, 0xc800
	s_nop 0
	global_load_lds_dwordx4 v[246:247], off
	v_lshl_add_u64 v[248:249], v[134:135], 0, s[48:49]
	v_lshl_add_u64 v[248:249], v[248:249], 0, s[52:53]
	v_lshl_add_u64 v[248:249], v[248:249], 0, s[54:55]
	s_add_i32 m0, s4, 0xcc00
	s_nop 0
	global_load_lds_dwordx4 v[248:249], off
	v_lshl_add_u64 v[246:247], v[128:129], 0, s[50:51]
	s_add_i32 m0, s63, 0x0
	s_nop 0
	global_load_lds_dwordx4 v[246:247], off
	v_lshl_add_u64 v[248:249], v[130:131], 0, s[50:51]
	s_add_i32 m0, s63, 0x400
	s_nop 0
	global_load_lds_dwordx4 v[248:249], off
	s_setprio 1
	s_waitcnt lgkmcnt(6)
	v_mfma_f32_32x32x16_bf16 v[64:79], v[188:191], v[140:143], v[64:79]
	s_waitcnt lgkmcnt(5)
	v_mfma_f32_32x32x16_bf16 v[80:95], v[204:207], v[140:143], v[80:95]
	s_waitcnt lgkmcnt(4)
	v_mfma_f32_32x32x16_bf16 v[112:127], v[188:191], v[164:167], v[112:127]
	v_mfma_f32_32x32x16_bf16 v[96:111], v[204:207], v[164:167], v[96:111]
	ds_read_b128 v[148:151], v138 offset:16384
	ds_read_b128 v[196:199], v237 offset:32768
	ds_read_b128 v[238:241], v237 offset:36864
	ds_read_b128 v[180:183], v138 offset:20480
	s_waitcnt lgkmcnt(6)
	v_mfma_f32_32x32x16_bf16 v[64:79], v[192:195], v[144:147], v[64:79]
	s_waitcnt lgkmcnt(5)
	v_mfma_f32_32x32x16_bf16 v[80:95], v[208:211], v[144:147], v[80:95]
	s_waitcnt lgkmcnt(4)
	v_mfma_f32_32x32x16_bf16 v[112:127], v[192:195], v[170:173], v[112:127]
	v_mfma_f32_32x32x16_bf16 v[96:111], v[208:211], v[170:173], v[96:111]
	ds_read_b128 v[160:163], v139 offset:16384
	ds_read_b128 v[200:203], v252 offset:32768
	ds_read_b128 v[242:245], v252 offset:36864
	ds_read_b128 v[184:187], v139 offset:20480
	s_waitcnt lgkmcnt(6)
	v_mfma_f32_32x32x16_bf16 v[64:79], v[196:199], v[148:151], v[64:79]
	s_waitcnt lgkmcnt(5)
	v_mfma_f32_32x32x16_bf16 v[80:95], v[238:241], v[148:151], v[80:95]
	s_waitcnt lgkmcnt(4)
	v_mfma_f32_32x32x16_bf16 v[112:127], v[196:199], v[180:183], v[112:127]
	v_mfma_f32_32x32x16_bf16 v[96:111], v[238:241], v[180:183], v[96:111]
	s_waitcnt lgkmcnt(2)
	v_mfma_f32_32x32x16_bf16 v[64:79], v[200:203], v[160:163], v[64:79]
	s_waitcnt lgkmcnt(1)
	v_mfma_f32_32x32x16_bf16 v[80:95], v[242:245], v[160:163], v[80:95]
	s_waitcnt lgkmcnt(0)
	v_mfma_f32_32x32x16_bf16 v[112:127], v[200:203], v[184:187], v[112:127]
	v_mfma_f32_32x32x16_bf16 v[96:111], v[242:245], v[184:187], v[96:111]
	s_setprio 0
	s_waitcnt vmcnt(2)
	s_barrier
	ds_read_b128 v[188:191], v232 offset:49152
	ds_read_b128 v[204:207], v232 offset:53248
	ds_read_b128 v[192:195], v233 offset:49152
	ds_read_b128 v[208:211], v233 offset:53248
	ds_read_b128 v[196:199], v237 offset:49152
	ds_read_b128 v[238:241], v237 offset:53248
	ds_read_b128 v[200:203], v252 offset:49152
	ds_read_b128 v[242:245], v252 offset:53248
	v_lshl_add_u64 v[246:247], v[132:133], 0, s[50:51]
	s_add_i32 m0, s4, 0x8000
	s_nop 0
	global_load_lds_dwordx4 v[246:247], off
	v_lshl_add_u64 v[248:249], v[134:135], 0, s[50:51]
	s_add_i32 m0, s4, 0x8400
	s_nop 0
	global_load_lds_dwordx4 v[248:249], off
	v_lshl_add_u64 v[246:247], v[132:133], 0, s[50:51]
	v_lshl_add_u64 v[246:247], v[246:247], 0, s[54:55]
	s_add_i32 m0, s4, 0x8800
	s_nop 0
	global_load_lds_dwordx4 v[246:247], off
	v_lshl_add_u64 v[248:249], v[134:135], 0, s[50:51]
	v_lshl_add_u64 v[248:249], v[248:249], 0, s[54:55]
	s_add_i32 m0, s4, 0x8c00
	s_nop 0
	global_load_lds_dwordx4 v[248:249], off
	v_lshl_add_u64 v[246:247], v[128:129], 0, s[50:51]
	v_lshl_add_u64 v[246:247], v[246:247], 0, s[52:53]
	s_add_i32 m0, s63, 0x2000
	s_nop 0
	global_load_lds_dwordx4 v[246:247], off
	v_lshl_add_u64 v[248:249], v[130:131], 0, s[50:51]
	v_lshl_add_u64 v[248:249], v[248:249], 0, s[52:53]
	s_add_i32 m0, s63, 0x2400
	s_nop 0
	global_load_lds_dwordx4 v[248:249], off
	s_add_u32 s48, s48, 0x80
	s_addc_u32 s49, s49, 0
	s_add_u32 s50, s50, 0x80
	s_addc_u32 s51, s51, 0
	s_setprio 1
	s_waitcnt lgkmcnt(7)
	v_mfma_f32_32x32x16_bf16 v[16:31], v[188:191], v[140:143], v[16:31]
	s_waitcnt lgkmcnt(6)
	v_mfma_f32_32x32x16_bf16 v[0:15], v[204:207], v[140:143], v[0:15]
	v_mfma_f32_32x32x16_bf16 v[48:63], v[188:191], v[164:167], v[48:63]
	v_mfma_f32_32x32x16_bf16 v[32:47], v[204:207], v[164:167], v[32:47]
	s_waitcnt lgkmcnt(5)
	v_mfma_f32_32x32x16_bf16 v[16:31], v[192:195], v[144:147], v[16:31]
	s_waitcnt lgkmcnt(4)
	v_mfma_f32_32x32x16_bf16 v[0:15], v[208:211], v[144:147], v[0:15]
	v_mfma_f32_32x32x16_bf16 v[48:63], v[192:195], v[170:173], v[48:63]
	v_mfma_f32_32x32x16_bf16 v[32:47], v[208:211], v[170:173], v[32:47]
	s_waitcnt lgkmcnt(3)
	v_mfma_f32_32x32x16_bf16 v[16:31], v[196:199], v[148:151], v[16:31]
	s_waitcnt lgkmcnt(2)
	v_mfma_f32_32x32x16_bf16 v[0:15], v[238:241], v[148:151], v[0:15]
	v_mfma_f32_32x32x16_bf16 v[48:63], v[196:199], v[180:183], v[48:63]
	v_mfma_f32_32x32x16_bf16 v[32:47], v[238:241], v[180:183], v[32:47]
	s_waitcnt lgkmcnt(1)
	v_mfma_f32_32x32x16_bf16 v[16:31], v[200:203], v[160:163], v[16:31]
	s_waitcnt lgkmcnt(0)
	v_mfma_f32_32x32x16_bf16 v[0:15], v[242:245], v[160:163], v[0:15]
	v_mfma_f32_32x32x16_bf16 v[48:63], v[200:203], v[184:187], v[48:63]
	v_mfma_f32_32x32x16_bf16 v[32:47], v[242:245], v[184:187], v[32:47]
	s_setprio 0
	s_add_i32 s5, s5, -1
	s_cmp_lg_u32 s5, 0
	s_cbranch_scc1 .Lk4_loop
	s_waitcnt vmcnt(0)
	s_barrier
	ds_read_b128 v[140:143], v136 offset:0
	ds_read_b128 v[188:191], v232 offset:32768
	ds_read_b128 v[204:207], v232 offset:36864
	ds_read_b128 v[164:167], v136 offset:4096
	ds_read_b128 v[144:147], v137 offset:0
	ds_read_b128 v[192:195], v233 offset:32768
	ds_read_b128 v[208:211], v233 offset:36864
	ds_read_b128 v[170:173], v137 offset:4096
	v_lshl_add_u64 v[246:247], v[132:133], 0, s[48:49]
	v_lshl_add_u64 v[246:247], v[246:247], 0, s[52:53]
	s_add_i32 m0, s4, 0xc000
	s_nop 0
	global_load_lds_dwordx4 v[246:247], off
	v_lshl_add_u64 v[248:249], v[134:135], 0, s[48:49]
	v_lshl_add_u64 v[248:249], v[248:249], 0, s[52:53]
	s_add_i32 m0, s4, 0xc400
	s_nop 0
	global_load_lds_dwordx4 v[248:249], off
	v_lshl_add_u64 v[246:247], v[132:133], 0, s[48:49]
	v_lshl_add_u64 v[246:247], v[246:247], 0, s[52:53]
	v_lshl_add_u64 v[246:247], v[246:247], 0, s[54:55]
	s_add_i32 m0, s4, 0xc800
	s_nop 0
	global_load_lds_dwordx4 v[246:247], off
	v_lshl_add_u64 v[248:249], v[134:135], 0, s[48:49]
	v_lshl_add_u64 v[248:249], v[248:249], 0, s[52:53]
	v_lshl_add_u64 v[248:249], v[248:249], 0, s[54:55]
	s_add_i32 m0, s4, 0xcc00
	s_nop 0
	global_load_lds_dwordx4 v[248:249], off
	v_lshl_add_u64 v[246:247], v[128:129], 0, s[50:51]
	s_add_i32 m0, s63, 0x4000
	s_nop 0
	global_load_lds_dwordx4 v[246:247], off
	v_lshl_add_u64 v[248:249], v[130:131], 0, s[50:51]
	s_add_i32 m0, s63, 0x4400
	s_nop 0
	global_load_lds_dwordx4 v[248:249], off
	s_setprio 1
	s_waitcnt lgkmcnt(6)
	v_mfma_f32_32x32x16_bf16 v[64:79], v[188:191], v[140:143], v[64:79]
	s_waitcnt lgkmcnt(5)
	v_mfma_f32_32x32x16_bf16 v[80:95], v[204:207], v[140:143], v[80:95]
	s_waitcnt lgkmcnt(4)
	v_mfma_f32_32x32x16_bf16 v[112:127], v[188:191], v[164:167], v[112:127]
	v_mfma_f32_32x32x16_bf16 v[96:111], v[204:207], v[164:167], v[96:111]
	ds_read_b128 v[148:151], v138 offset:0
	ds_read_b128 v[196:199], v237 offset:32768
	ds_read_b128 v[238:241], v237 offset:36864
	ds_read_b128 v[180:183], v138 offset:4096
	s_waitcnt lgkmcnt(6)
	v_mfma_f32_32x32x16_bf16 v[64:79], v[192:195], v[144:147], v[64:79]
	s_waitcnt lgkmcnt(5)
	v_mfma_f32_32x32x16_bf16 v[80:95], v[208:211], v[144:147], v[80:95]
	s_waitcnt lgkmcnt(4)
	v_mfma_f32_32x32x16_bf16 v[112:127], v[192:195], v[170:173], v[112:127]
	v_mfma_f32_32x32x16_bf16 v[96:111], v[208:211], v[170:173], v[96:111]
	ds_read_b128 v[160:163], v139 offset:0
	ds_read_b128 v[200:203], v252 offset:32768
	ds_read_b128 v[242:245], v252 offset:36864
	ds_read_b128 v[184:187], v139 offset:4096
	s_waitcnt lgkmcnt(6)
	v_mfma_f32_32x32x16_bf16 v[64:79], v[196:199], v[148:151], v[64:79]
	s_waitcnt lgkmcnt(5)
	v_mfma_f32_32x32x16_bf16 v[80:95], v[238:241], v[148:151], v[80:95]
	s_waitcnt lgkmcnt(4)
	v_mfma_f32_32x32x16_bf16 v[112:127], v[196:199], v[180:183], v[112:127]
	v_mfma_f32_32x32x16_bf16 v[96:111], v[238:241], v[180:183], v[96:111]
	s_waitcnt lgkmcnt(2)
	v_mfma_f32_32x32x16_bf16 v[64:79], v[200:203], v[160:163], v[64:79]
	s_waitcnt lgkmcnt(1)
	v_mfma_f32_32x32x16_bf16 v[80:95], v[242:245], v[160:163], v[80:95]
	s_waitcnt lgkmcnt(0)
	v_mfma_f32_32x32x16_bf16 v[112:127], v[200:203], v[184:187], v[112:127]
	v_mfma_f32_32x32x16_bf16 v[96:111], v[242:245], v[184:187], v[96:111]
	s_setprio 0
	s_waitcnt vmcnt(2)
	s_barrier
	ds_read_b128 v[188:191], v232 offset:49152
	ds_read_b128 v[204:207], v232 offset:53248
	ds_read_b128 v[192:195], v233 offset:49152
	ds_read_b128 v[208:211], v233 offset:53248
	ds_read_b128 v[196:199], v237 offset:49152
	ds_read_b128 v[238:241], v237 offset:53248
	ds_read_b128 v[200:203], v252 offset:49152
	ds_read_b128 v[242:245], v252 offset:53248
	v_lshl_add_u64 v[246:247], v[132:133], 0, s[50:51]
	s_add_i32 m0, s4, 0x8000
	s_nop 0
	global_load_lds_dwordx4 v[246:247], off
	v_lshl_add_u64 v[248:249], v[134:135], 0, s[50:51]
	s_add_i32 m0, s4, 0x8400
	s_nop 0
	global_load_lds_dwordx4 v[248:249], off
	v_lshl_add_u64 v[246:247], v[132:133], 0, s[50:51]
	v_lshl_add_u64 v[246:247], v[246:247], 0, s[54:55]
	s_add_i32 m0, s4, 0x8800
	s_nop 0
	global_load_lds_dwordx4 v[246:247], off
	v_lshl_add_u64 v[248:249], v[134:135], 0, s[50:51]
	v_lshl_add_u64 v[248:249], v[248:249], 0, s[54:55]
	s_add_i32 m0, s4, 0x8c00
	s_nop 0
	global_load_lds_dwordx4 v[248:249], off
	v_lshl_add_u64 v[246:247], v[128:129], 0, s[50:51]
	v_lshl_add_u64 v[246:247], v[246:247], 0, s[52:53]
	s_add_i32 m0, s63, 0x6000
	s_nop 0
	global_load_lds_dwordx4 v[246:247], off
	v_lshl_add_u64 v[248:249], v[130:131], 0, s[50:51]
	v_lshl_add_u64 v[248:249], v[248:249], 0, s[52:53]
	s_add_i32 m0, s63, 0x6400
	s_nop 0
	global_load_lds_dwordx4 v[248:249], off
	s_add_u32 s48, s48, 0x80
	s_addc_u32 s49, s49, 0
	s_add_u32 s50, s50, 0x80
	s_addc_u32 s51, s51, 0
	s_setprio 1
	s_waitcnt lgkmcnt(7)
	v_mfma_f32_32x32x16_bf16 v[16:31], v[188:191], v[140:143], v[16:31]
	s_waitcnt lgkmcnt(6)
	v_mfma_f32_32x32x16_bf16 v[0:15], v[204:207], v[140:143], v[0:15]
	v_mfma_f32_32x32x16_bf16 v[48:63], v[188:191], v[164:167], v[48:63]
	v_mfma_f32_32x32x16_bf16 v[32:47], v[204:207], v[164:167], v[32:47]
	s_waitcnt lgkmcnt(5)
	v_mfma_f32_32x32x16_bf16 v[16:31], v[192:195], v[144:147], v[16:31]
	s_waitcnt lgkmcnt(4)
	v_mfma_f32_32x32x16_bf16 v[0:15], v[208:211], v[144:147], v[0:15]
	v_mfma_f32_32x32x16_bf16 v[48:63], v[192:195], v[170:173], v[48:63]
	v_mfma_f32_32x32x16_bf16 v[32:47], v[208:211], v[170:173], v[32:47]
	s_waitcnt lgkmcnt(3)
	v_mfma_f32_32x32x16_bf16 v[16:31], v[196:199], v[148:151], v[16:31]
	s_waitcnt lgkmcnt(2)
	v_mfma_f32_32x32x16_bf16 v[0:15], v[238:241], v[148:151], v[0:15]
	v_mfma_f32_32x32x16_bf16 v[48:63], v[196:199], v[180:183], v[48:63]
	v_mfma_f32_32x32x16_bf16 v[32:47], v[238:241], v[180:183], v[32:47]
	s_waitcnt lgkmcnt(1)
	v_mfma_f32_32x32x16_bf16 v[16:31], v[200:203], v[160:163], v[16:31]
	s_waitcnt lgkmcnt(0)
	v_mfma_f32_32x32x16_bf16 v[0:15], v[242:245], v[160:163], v[0:15]
	v_mfma_f32_32x32x16_bf16 v[48:63], v[200:203], v[184:187], v[48:63]
	v_mfma_f32_32x32x16_bf16 v[32:47], v[242:245], v[184:187], v[32:47]
	s_setprio 0
	s_waitcnt vmcnt(0)
	s_barrier
	ds_read_b128 v[140:143], v136 offset:16384
	ds_read_b128 v[188:191], v232 offset:32768
	ds_read_b128 v[204:207], v232 offset:36864
	ds_read_b128 v[164:167], v136 offset:20480
	ds_read_b128 v[144:147], v137 offset:16384
	ds_read_b128 v[192:195], v233 offset:32768
	ds_read_b128 v[208:211], v233 offset:36864
	ds_read_b128 v[170:173], v137 offset:20480
	v_lshl_add_u64 v[246:247], v[132:133], 0, s[48:49]
	v_lshl_add_u64 v[246:247], v[246:247], 0, s[52:53]
	s_add_i32 m0, s4, 0xc000
	s_nop 0
	global_load_lds_dwordx4 v[246:247], off
	v_lshl_add_u64 v[248:249], v[134:135], 0, s[48:49]
	v_lshl_add_u64 v[248:249], v[248:249], 0, s[52:53]
	s_add_i32 m0, s4, 0xc400
	s_nop 0
	global_load_lds_dwordx4 v[248:249], off
	v_lshl_add_u64 v[246:247], v[132:133], 0, s[48:49]
	v_lshl_add_u64 v[246:247], v[246:247], 0, s[52:53]
	v_lshl_add_u64 v[246:247], v[246:247], 0, s[54:55]
	s_add_i32 m0, s4, 0xc800
	s_nop 0
	global_load_lds_dwordx4 v[246:247], off
	v_lshl_add_u64 v[248:249], v[134:135], 0, s[48:49]
	v_lshl_add_u64 v[248:249], v[248:249], 0, s[52:53]
	v_lshl_add_u64 v[248:249], v[248:249], 0, s[54:55]
	s_add_i32 m0, s4, 0xcc00
	s_nop 0
	global_load_lds_dwordx4 v[248:249], off
	s_setprio 1
	s_waitcnt lgkmcnt(6)
	v_mfma_f32_32x32x16_bf16 v[64:79], v[188:191], v[140:143], v[64:79]
	s_waitcnt lgkmcnt(5)
	v_mfma_f32_32x32x16_bf16 v[80:95], v[204:207], v[140:143], v[80:95]
	s_waitcnt lgkmcnt(4)
	v_mfma_f32_32x32x16_bf16 v[112:127], v[188:191], v[164:167], v[112:127]
	v_mfma_f32_32x32x16_bf16 v[96:111], v[204:207], v[164:167], v[96:111]
	ds_read_b128 v[148:151], v138 offset:16384
	ds_read_b128 v[196:199], v237 offset:32768
	ds_read_b128 v[238:241], v237 offset:36864
	ds_read_b128 v[180:183], v138 offset:20480
	s_waitcnt lgkmcnt(6)
	v_mfma_f32_32x32x16_bf16 v[64:79], v[192:195], v[144:147], v[64:79]
	s_waitcnt lgkmcnt(5)
	v_mfma_f32_32x32x16_bf16 v[80:95], v[208:211], v[144:147], v[80:95]
	s_waitcnt lgkmcnt(4)
	v_mfma_f32_32x32x16_bf16 v[112:127], v[192:195], v[170:173], v[112:127]
	v_mfma_f32_32x32x16_bf16 v[96:111], v[208:211], v[170:173], v[96:111]
	ds_read_b128 v[160:163], v139 offset:16384
	ds_read_b128 v[200:203], v252 offset:32768
	ds_read_b128 v[242:245], v252 offset:36864
	ds_read_b128 v[184:187], v139 offset:20480
	s_waitcnt lgkmcnt(6)
	v_mfma_f32_32x32x16_bf16 v[64:79], v[196:199], v[148:151], v[64:79]
	s_waitcnt lgkmcnt(5)
	v_mfma_f32_32x32x16_bf16 v[80:95], v[238:241], v[148:151], v[80:95]
	s_waitcnt lgkmcnt(4)
	v_mfma_f32_32x32x16_bf16 v[112:127], v[196:199], v[180:183], v[112:127]
	v_mfma_f32_32x32x16_bf16 v[96:111], v[238:241], v[180:183], v[96:111]
	s_waitcnt lgkmcnt(2)
	v_mfma_f32_32x32x16_bf16 v[64:79], v[200:203], v[160:163], v[64:79]
	s_waitcnt lgkmcnt(1)
	v_mfma_f32_32x32x16_bf16 v[80:95], v[242:245], v[160:163], v[80:95]
	s_waitcnt lgkmcnt(0)
	v_mfma_f32_32x32x16_bf16 v[112:127], v[200:203], v[184:187], v[112:127]
	v_mfma_f32_32x32x16_bf16 v[96:111], v[242:245], v[184:187], v[96:111]
	s_setprio 0
	s_waitcnt vmcnt(0)
	s_barrier
	ds_read_b128 v[188:191], v232 offset:49152
	ds_read_b128 v[204:207], v232 offset:53248
	ds_read_b128 v[192:195], v233 offset:49152
	ds_read_b128 v[208:211], v233 offset:53248
	ds_read_b128 v[196:199], v237 offset:49152
	ds_read_b128 v[238:241], v237 offset:53248
	ds_read_b128 v[200:203], v252 offset:49152
	ds_read_b128 v[242:245], v252 offset:53248
	s_setprio 1
	s_waitcnt lgkmcnt(7)
	v_mfma_f32_32x32x16_bf16 v[16:31], v[188:191], v[140:143], v[16:31]
	s_waitcnt lgkmcnt(6)
	v_mfma_f32_32x32x16_bf16 v[0:15], v[204:207], v[140:143], v[0:15]
	v_mfma_f32_32x32x16_bf16 v[48:63], v[188:191], v[164:167], v[48:63]
	v_mfma_f32_32x32x16_bf16 v[32:47], v[204:207], v[164:167], v[32:47]
	s_waitcnt lgkmcnt(5)
	v_mfma_f32_32x32x16_bf16 v[16:31], v[192:195], v[144:147], v[16:31]
	s_waitcnt lgkmcnt(4)
	v_mfma_f32_32x32x16_bf16 v[0:15], v[208:211], v[144:147], v[0:15]
	v_mfma_f32_32x32x16_bf16 v[48:63], v[192:195], v[170:173], v[48:63]
	v_mfma_f32_32x32x16_bf16 v[32:47], v[208:211], v[170:173], v[32:47]
	s_waitcnt lgkmcnt(3)
	v_mfma_f32_32x32x16_bf16 v[16:31], v[196:199], v[148:151], v[16:31]
	s_waitcnt lgkmcnt(2)
	v_mfma_f32_32x32x16_bf16 v[0:15], v[238:241], v[148:151], v[0:15]
	v_mfma_f32_32x32x16_bf16 v[48:63], v[196:199], v[180:183], v[48:63]
	v_mfma_f32_32x32x16_bf16 v[32:47], v[238:241], v[180:183], v[32:47]
	s_waitcnt lgkmcnt(1)
	v_mfma_f32_32x32x16_bf16 v[16:31], v[200:203], v[160:163], v[16:31]
	s_waitcnt lgkmcnt(0)
	v_mfma_f32_32x32x16_bf16 v[0:15], v[242:245], v[160:163], v[0:15]
	v_mfma_f32_32x32x16_bf16 v[48:63], v[200:203], v[184:187], v[48:63]
	v_mfma_f32_32x32x16_bf16 v[32:47], v[242:245], v[184:187], v[32:47]
	s_setprio 0

.LBB0_771:
	s_and_b32 s6, 0xffff, s14
	s_mul_hi_u32 s6, s6, 0x1745d18
	s_lshl_b32 s7, s6, 3
	s_mulk_i32 s6, 0x1600
	s_sub_i32 s6, s12, s6
	s_add_i32 s7, s89, s7
	s_and_b32 s8, s13, 7
	s_and_b32 s6, s6, 0xffffff00
	s_add_i32 s41, s7, s8
	s_ashr_i32 s7, s6, 31
	s_lshl_b64 s[8:9], s[6:7], 11
	s_mul_i32 s6, s15, 0xba2f
	s_lshr_b32 s6, s6, 23
	v_mov_b32_e32 v152, v179
	s_mul_i32 s7, s6, 0xffffff50
	s_lshl_b32 s6, s6, 3
	s_add_i32 s6, s6, s89
	v_readfirstlane_b32 s42, v152
	s_and_b32 s10, s15, 7
	s_ashr_i32 s21, s42, 6
	v_and_b32_e32 v1, 60, v152
	s_add_i32 s7, s7, s15
	s_or_b32 s6, s6, s10
	v_lshl_or_b32 v1, s21, 7, v1
	s_lshl_b32 s16, s6, 7
	s_lshl_b32 s6, s7, 5
	v_bfe_u32 v154, v152, 2, 4
	s_and_b32 s7, s42, 0x3fffc0
	v_ashrrev_i32_e32 v16, 2, v1
	s_and_b32 s6, s6, 0xffffff00
	v_lshrrev_b32_e32 v12, 4, v152
	v_or_b32_e32 v2, s7, v154
	s_lshl_b32 s7, s21, 11
	s_waitcnt vmcnt(0)
	v_add_u32_e32 v8, s16, v16
	v_xor_b32_e32 v0, v12, v152
	s_add_i32 s19, s7, 16
	v_ashrrev_i32_e32 v9, 31, v8
	s_ashr_i32 s7, s6, 31
	s_ashr_i32 s17, s42, 7
	s_and_b32 s18, s21, 1
	v_lshlrev_b32_e32 v0, 3, v0
	v_lshlrev_b64 v[10:11], 11, v[8:9]
	v_or_b32_e32 v8, 16, v8
	s_add_i32 s20, s19, 0x400
	s_lshl_b64 s[10:11], s[6:7], 11
	v_readlane_b32 s7, v253, 63
	v_and_b32_e32 v13, 24, v0
	v_ashrrev_i32_e32 v9, 31, v8
	s_add_u32 s10, s7, s10
	v_readlane_b32 s7, v254, 0
	v_lshl_add_u64 v[10:11], s[80:81], 0, v[10:11]
	v_lshlrev_b32_e32 v176, 1, v13
	v_lshlrev_b64 v[8:9], 11, v[8:9]
	s_addc_u32 s11, s7, s11
	s_lshl_b32 s7, s21, 12
	v_lshl_or_b32 v0, v2, 10, v13
	v_lshl_add_u64 v[10:11], v[10:11], 0, v[176:177]
	s_mov_b32 m0, s19
	v_lshl_add_u64 v[8:9], s[80:81], 0, v[8:9]
	s_add_i32 s7, s7, 16
	v_or_b32_e32 v2, 0x4000, v0
	v_bfe_u32 v155, v152, 5, 1
	v_lshrrev_b32_e32 v3, 2, v152
	v_lshl_add_u64 v[8:9], v[8:9], 0, v[176:177]
	s_mov_b32 m0, s20
	s_add_i32 s21, s7, 0x2000
	v_ashrrev_i32_e32 v1, 31, v0
	v_or_b32_e32 v4, 0x8000, v0
	v_or_b32_e32 v6, 0xc000, v0
	v_bfe_u32 v5, v152, 2, 2
	v_bitop3_b32 v14, v155, v3, 3 bitop3:0x78
	v_lshl_add_u64 v[0:1], v[0:1], 1, s[10:11]
	s_mov_b32 m0, s21
	v_ashrrev_i32_e32 v3, 31, v2
	s_add_i32 s24, s7, 0x2400
	v_bitop3_b32 v15, v155, v5, 2 bitop3:0x36
	v_lshl_add_u64 v[0:1], v[2:3], 1, s[10:11]
	s_mov_b32 m0, s24
	v_ashrrev_i32_e32 v5, 31, v4
	s_add_i32 s25, s7, 0x2800
	v_lshl_add_u64 v[0:1], v[4:5], 1, s[10:11]
	s_mov_b32 m0, s25
	v_ashrrev_i32_e32 v7, 31, v6
	s_add_i32 s37, s7, 0x2c00
	v_lshl_add_u64 v[0:1], v[6:7], 1, s[10:11]
	s_mov_b32 m0, s37
	s_lshl_b32 s10, s18, 13
	v_lshl_add_u32 v0, v14, 4, 16
	s_lshl_b32 s11, s17, 12
	v_add_u32_e32 v5, s11, v0
	v_add_u32_e32 v6, s10, v0
	v_lshl_add_u32 v0, v15, 4, 16
	v_add_u32_e32 v7, s11, v0
	v_add_u32_e32 v8, s10, v0
	v_lshl_add_u32 v0, s41, 7, v16
	v_ashrrev_i32_e32 v1, 31, v0
	v_lshlrev_b64 v[128:129], 11, v[0:1]
	v_bitop3_b32 v1, v12, 3, v152 bitop3:0x48
	v_or_b32_e32 v0, 16, v0
	v_lshlrev_b32_e32 v2, 4, v1
	v_ashrrev_i32_e32 v1, 31, v0
	s_lshl_b32 s10, s42, 10
	v_lshlrev_b64 v[130:131], 11, v[0:1]
	s_and_b32 s10, s10, 0xffff0000
	v_lshlrev_b32_e32 v0, 10, v154
	v_or3_b32 v0, v0, s10, v13
	v_or_b32_e32 v128, v128, v2
	v_or_b32_e32 v130, v130, v2
	v_or_b32_e32 v2, 0x4000, v0
	v_ashrrev_i32_e32 v1, 31, v0
	v_ashrrev_i32_e32 v3, 31, v2
	v_and_b32_e32 v153, 31, v152
	v_lshl_add_u64 v[132:133], v[0:1], 1, s[8:9]
	v_lshl_add_u64 v[134:135], v[2:3], 1, s[8:9]
	v_or_b32_e32 v2, 0x8000, v0
	v_or_b32_e32 v0, 0xc000, v0
	v_lshlrev_b32_e32 v4, 6, v153
	v_ashrrev_i32_e32 v3, 31, v2
	v_ashrrev_i32_e32 v1, 31, v0
	v_mov_b32_e32 v96, 0
	v_lshl_add_u64 v[136:137], v[2:3], 1, s[8:9]
	v_lshl_add_u64 v[138:139], v[0:1], 1, s[8:9]
	s_mov_b32 s41, 0
	v_add_u32_e32 v156, v5, v4
	v_add_u32_e32 v157, v6, v4
	v_add_u32_e32 v158, v7, v4
	v_add_u32_e32 v159, v8, v4
	s_mov_b64 s[8:9], s[80:81]
	v_mov_b32_e32 v97, v96
	v_mov_b32_e32 v98, v96
	v_mov_b32_e32 v99, v96
	v_mov_b32_e32 v100, v96
	v_mov_b32_e32 v101, v96
	v_mov_b32_e32 v102, v96
	v_mov_b32_e32 v103, v96
	v_mov_b32_e32 v104, v96
	v_mov_b32_e32 v105, v96
	v_mov_b32_e32 v106, v96
	v_mov_b32_e32 v107, v96
	v_mov_b32_e32 v108, v96
	v_mov_b32_e32 v109, v96
	v_mov_b32_e32 v110, v96
	v_mov_b32_e32 v111, v96
	v_mov_b32_e32 v112, v96
	v_mov_b32_e32 v113, v96
	v_mov_b32_e32 v114, v96
	v_mov_b32_e32 v115, v96
	v_mov_b32_e32 v116, v96
	v_mov_b32_e32 v117, v96
	v_mov_b32_e32 v118, v96
	v_mov_b32_e32 v119, v96
	v_mov_b32_e32 v120, v96
	v_mov_b32_e32 v121, v96
	v_mov_b32_e32 v122, v96
	v_mov_b32_e32 v123, v96
	v_mov_b32_e32 v124, v96
	v_mov_b32_e32 v125, v96
	v_mov_b32_e32 v126, v96
	v_mov_b32_e32 v127, v96
	v_mov_b32_e32 v32, v96
	v_mov_b32_e32 v33, v96
	v_mov_b32_e32 v34, v96
	v_mov_b32_e32 v35, v96
	v_mov_b32_e32 v36, v96
	v_mov_b32_e32 v37, v96
	v_mov_b32_e32 v38, v96
	v_mov_b32_e32 v39, v96
	v_mov_b32_e32 v40, v96
	v_mov_b32_e32 v41, v96
	v_mov_b32_e32 v42, v96
	v_mov_b32_e32 v43, v96
	v_mov_b32_e32 v44, v96
	v_mov_b32_e32 v45, v96
	v_mov_b32_e32 v46, v96
	v_mov_b32_e32 v47, v96
	v_mov_b32_e32 v48, v96
	v_mov_b32_e32 v49, v96
	v_mov_b32_e32 v50, v96
	v_mov_b32_e32 v51, v96
	v_mov_b32_e32 v52, v96
	v_mov_b32_e32 v53, v96
	v_mov_b32_e32 v54, v96
	v_mov_b32_e32 v55, v96
	v_mov_b32_e32 v56, v96
	v_mov_b32_e32 v57, v96
	v_mov_b32_e32 v58, v96
	v_mov_b32_e32 v59, v96
	v_mov_b32_e32 v60, v96
	v_mov_b32_e32 v61, v96
	v_mov_b32_e32 v62, v96
	v_mov_b32_e32 v63, v96
	v_mov_b32_e32 v64, v96
	v_mov_b32_e32 v65, v96
	v_mov_b32_e32 v66, v96
	v_mov_b32_e32 v67, v96
	v_mov_b32_e32 v68, v96
	v_mov_b32_e32 v69, v96
	v_mov_b32_e32 v70, v96
	v_mov_b32_e32 v71, v96
	v_mov_b32_e32 v72, v96
	v_mov_b32_e32 v73, v96
	v_mov_b32_e32 v74, v96
	v_mov_b32_e32 v75, v96
	v_mov_b32_e32 v76, v96
	v_mov_b32_e32 v77, v96
	v_mov_b32_e32 v78, v96
	v_mov_b32_e32 v79, v96
	v_mov_b32_e32 v80, v96
	v_mov_b32_e32 v81, v96
	v_mov_b32_e32 v82, v96
	v_mov_b32_e32 v83, v96
	v_mov_b32_e32 v84, v96
	v_mov_b32_e32 v85, v96
	v_mov_b32_e32 v86, v96
	v_mov_b32_e32 v87, v96
	v_mov_b32_e32 v88, v96
	v_mov_b32_e32 v89, v96
	v_mov_b32_e32 v90, v96
	v_mov_b32_e32 v91, v96
	v_mov_b32_e32 v92, v96
	v_mov_b32_e32 v93, v96
	v_mov_b32_e32 v94, v96
	v_mov_b32_e32 v95, v96
	v_mov_b32_e32 v0, v96
	v_mov_b32_e32 v1, v96
	v_mov_b32_e32 v2, v96
	v_mov_b32_e32 v3, v96
	v_mov_b32_e32 v4, v96
	v_mov_b32_e32 v5, v96
	v_mov_b32_e32 v6, v96
	v_mov_b32_e32 v7, v96
	v_mov_b32_e32 v8, v96
	v_mov_b32_e32 v9, v96
	v_mov_b32_e32 v10, v96
	v_mov_b32_e32 v11, v96
	v_mov_b32_e32 v12, v96
	v_mov_b32_e32 v13, v96
	v_mov_b32_e32 v14, v96
	v_mov_b32_e32 v15, v96
	v_mov_b32_e32 v16, v96
	v_mov_b32_e32 v17, v96
	v_mov_b32_e32 v18, v96
	v_mov_b32_e32 v19, v96
	v_mov_b32_e32 v20, v96
	v_mov_b32_e32 v21, v96
	v_mov_b32_e32 v22, v96
	v_mov_b32_e32 v23, v96
	v_mov_b32_e32 v24, v96
	v_mov_b32_e32 v25, v96
	v_mov_b32_e32 v26, v96
	v_mov_b32_e32 v27, v96
	v_mov_b32_e32 v28, v96
	v_mov_b32_e32 v29, v96
	v_mov_b32_e32 v30, v96
	v_mov_b32_e32 v31, v96
	v_readfirstlane_b32 s62, v179
	v_readfirstlane_b32 s56, v128
	v_readfirstlane_b32 s57, v129
	v_readfirstlane_b32 s58, v132
	v_readfirstlane_b32 s59, v133
	s_lshr_b32 s62, s62, 6
	s_add_u32 s56, s56, s8
	s_addc_u32 s57, s57, s9
	s_add_u32 s58, s58, s8
	s_addc_u32 s59, s59, s9
	s_mul_i32 s25, s62, 0x8000
	s_sub_u32 s56, s56, s25
	s_subb_u32 s57, s57, 0
	s_and_b32 s25, s62, 1
	s_mul_i32 s25, s25, 0x10000
	s_sub_u32 s58, s58, s25
	s_subb_u32 s59, s59, 0
	s_add_u32 s58, s58, 0x7800000
	s_addc_u32 s59, s59, 0
	s_mov_b32 s24, 0x800
	v_and_b32_e32 v140, 63, v179
	v_lshrrev_b32_e32 v141, 3, v140
	v_lshrrev_b32_e32 v143, 4, v140
	v_and_b32_e32 v142, 7, v140
	v_xor_b32_e32 v142, v142, v143
	v_lshlrev_b32_e32 v142, 4, v142
	v_mad_u32_u24 v176, v141, s24, v142
	v_lshl_add_u64 v[128:129], s[56:57], 0, v[176:177]
	v_lshl_add_u64 v[132:133], s[58:59], 0, v[176:177]
	v_xor_b32_e32 v142, 64, v142
	v_mad_u32_u24 v176, v141, s24, v142
	s_add_u32 s60, s56, 0x4000
	s_addc_u32 s61, s57, 0
	v_lshl_add_u64 v[130:131], s[60:61], 0, v[176:177]
	s_add_u32 s60, s58, 0x4000
	s_addc_u32 s61, s59, 0
	s_nop 0
	v_lshl_add_u64 v[134:135], s[60:61], 0, v[176:177]
	v_and_b32_e32 v144, 31, v179
	v_bfe_u32 v145, v179, 5, 1
	v_bfe_u32 v143, v179, 1, 3
	v_xor_b32_e32 v145, v145, v143
	s_lshr_b32 s25, s62, 1
	s_lshl_b32 s25, s25, 13
	s_add_i32 s25, s25, 16
	v_lshl_add_u32 v146, v144, 7, s25
	s_and_b32 s25, s62, 1
	s_lshl_b32 s25, s25, 13
	s_add_i32 s25, s25, 16
	v_lshl_add_u32 v147, v144, 7, s25
	v_xor_b32_e32 v143, 0, v145
	v_lshl_add_u32 v136, v143, 4, v146
	v_lshl_add_u32 v232, v143, 4, v147
	v_xor_b32_e32 v143, 2, v145
	v_lshl_add_u32 v137, v143, 4, v146
	v_lshl_add_u32 v233, v143, 4, v147
	v_xor_b32_e32 v143, 4, v145
	v_lshl_add_u32 v138, v143, 4, v146
	v_lshl_add_u32 v237, v143, 4, v147
	v_xor_b32_e32 v143, 6, v145
	v_lshl_add_u32 v139, v143, 4, v146
	v_lshl_add_u32 v252, v143, 4, v147
	s_lshl_b32 s63, s62, 11
	s_add_i32 s63, s63, 16
	s_lshl_b32 s10, s62, 12
	s_add_i32 s10, s10, 16
	s_mov_b64 s[48:49], 0
	s_mov_b64 s[50:51], 0x80
	s_mov_b32 s52, 0x20000
	s_mov_b32 s53, 0
	s_mov_b32 s54, 0x8000
	s_mov_b32 s55, 0
	s_add_i32 m0, s63, 0x0
	s_nop 0
	global_load_lds_dwordx4 v[128:129], off
	s_add_i32 m0, s63, 0x400
	s_nop 0
	global_load_lds_dwordx4 v[130:131], off
	v_lshl_add_u64 v[246:247], v[128:129], 0, s[52:53]
	s_add_i32 m0, s63, 0x2000
	s_nop 0
	global_load_lds_dwordx4 v[246:247], off
	v_lshl_add_u64 v[248:249], v[130:131], 0, s[52:53]
	s_add_i32 m0, s63, 0x2400
	s_nop 0
	global_load_lds_dwordx4 v[248:249], off
	s_add_i32 m0, s10, 0x8000
	s_nop 0
	global_load_lds_dwordx4 v[132:133], off
	s_add_i32 m0, s10, 0x8400
	s_nop 0
	global_load_lds_dwordx4 v[134:135], off
	v_lshl_add_u64 v[246:247], v[132:133], 0, s[54:55]
	s_add_i32 m0, s10, 0x8800
	s_nop 0
	global_load_lds_dwordx4 v[246:247], off
	v_lshl_add_u64 v[248:249], v[134:135], 0, s[54:55]
	s_add_i32 m0, s10, 0x8c00
	s_nop 0
	global_load_lds_dwordx4 v[248:249], off
	s_movk_i32 s11, 7
.Lk3_loop:
	s_waitcnt vmcnt(0)
	s_barrier
	ds_read_b128 v[140:143], v136 offset:0
	ds_read_b128 v[188:191], v232 offset:32768
	ds_read_b128 v[204:207], v232 offset:36864
	ds_read_b128 v[164:167], v136 offset:4096
	ds_read_b128 v[144:147], v137 offset:0
	ds_read_b128 v[192:195], v233 offset:32768
	ds_read_b128 v[208:211], v233 offset:36864
	ds_read_b128 v[170:173], v137 offset:4096
	v_lshl_add_u64 v[246:247], v[132:133], 0, s[48:49]
	v_lshl_add_u64 v[246:247], v[246:247], 0, s[52:53]
	s_add_i32 m0, s10, 0xc000
	s_nop 0
	global_load_lds_dwordx4 v[246:247], off
	v_lshl_add_u64 v[248:249], v[134:135], 0, s[48:49]
	v_lshl_add_u64 v[248:249], v[248:249], 0, s[52:53]
	s_add_i32 m0, s10, 0xc400
	s_nop 0
	global_load_lds_dwordx4 v[248:249], off
	v_lshl_add_u64 v[246:247], v[132:133], 0, s[48:49]
	v_lshl_add_u64 v[246:247], v[246:247], 0, s[52:53]
	v_lshl_add_u64 v[246:247], v[246:247], 0, s[54:55]
	s_add_i32 m0, s10, 0xc800
	s_nop 0
	global_load_lds_dwordx4 v[246:247], off
	v_lshl_add_u64 v[248:249], v[134:135], 0, s[48:49]
	v_lshl_add_u64 v[248:249], v[248:249], 0, s[52:53]
	v_lshl_add_u64 v[248:249], v[248:249], 0, s[54:55]
	s_add_i32 m0, s10, 0xcc00
	s_nop 0
	global_load_lds_dwordx4 v[248:249], off
	v_lshl_add_u64 v[246:247], v[128:129], 0, s[50:51]
	s_add_i32 m0, s63, 0x4000
	s_nop 0
	global_load_lds_dwordx4 v[246:247], off
	v_lshl_add_u64 v[248:249], v[130:131], 0, s[50:51]
	s_add_i32 m0, s63, 0x4400
	s_nop 0
	global_load_lds_dwordx4 v[248:249], off
	s_setprio 1
	s_waitcnt lgkmcnt(6)
	v_mfma_f32_32x32x16_bf16 v[96:111], v[188:191], v[140:143], v[96:111]
	s_waitcnt lgkmcnt(5)
	v_mfma_f32_32x32x16_bf16 v[112:127], v[204:207], v[140:143], v[112:127]
	s_waitcnt lgkmcnt(4)
	v_mfma_f32_32x32x16_bf16 v[64:79], v[188:191], v[164:167], v[64:79]
	v_mfma_f32_32x32x16_bf16 v[80:95], v[204:207], v[164:167], v[80:95]
	ds_read_b128 v[148:151], v138 offset:0
	ds_read_b128 v[196:199], v237 offset:32768
	ds_read_b128 v[238:241], v237 offset:36864
	ds_read_b128 v[180:183], v138 offset:4096
	s_waitcnt lgkmcnt(6)
	v_mfma_f32_32x32x16_bf16 v[96:111], v[192:195], v[144:147], v[96:111]
	s_waitcnt lgkmcnt(5)
	v_mfma_f32_32x32x16_bf16 v[112:127], v[208:211], v[144:147], v[112:127]
	s_waitcnt lgkmcnt(4)
	v_mfma_f32_32x32x16_bf16 v[64:79], v[192:195], v[170:173], v[64:79]
	v_mfma_f32_32x32x16_bf16 v[80:95], v[208:211], v[170:173], v[80:95]
	ds_read_b128 v[160:163], v139 offset:0
	ds_read_b128 v[200:203], v252 offset:32768
	ds_read_b128 v[242:245], v252 offset:36864
	ds_read_b128 v[184:187], v139 offset:4096
	s_waitcnt lgkmcnt(6)
	v_mfma_f32_32x32x16_bf16 v[96:111], v[196:199], v[148:151], v[96:111]
	s_waitcnt lgkmcnt(5)
	v_mfma_f32_32x32x16_bf16 v[112:127], v[238:241], v[148:151], v[112:127]
	s_waitcnt lgkmcnt(4)
	v_mfma_f32_32x32x16_bf16 v[64:79], v[196:199], v[180:183], v[64:79]
	v_mfma_f32_32x32x16_bf16 v[80:95], v[238:241], v[180:183], v[80:95]
	s_waitcnt lgkmcnt(2)
	v_mfma_f32_32x32x16_bf16 v[96:111], v[200:203], v[160:163], v[96:111]
	s_waitcnt lgkmcnt(1)
	v_mfma_f32_32x32x16_bf16 v[112:127], v[242:245], v[160:163], v[112:127]
	s_waitcnt lgkmcnt(0)
	v_mfma_f32_32x32x16_bf16 v[64:79], v[200:203], v[184:187], v[64:79]
	v_mfma_f32_32x32x16_bf16 v[80:95], v[242:245], v[184:187], v[80:95]
	s_setprio 0
	s_waitcnt vmcnt(2)
	s_barrier
	ds_read_b128 v[188:191], v232 offset:49152
	ds_read_b128 v[204:207], v232 offset:53248
	ds_read_b128 v[192:195], v233 offset:49152
	ds_read_b128 v[208:211], v233 offset:53248
	ds_read_b128 v[196:199], v237 offset:49152
	ds_read_b128 v[238:241], v237 offset:53248
	ds_read_b128 v[200:203], v252 offset:49152
	ds_read_b128 v[242:245], v252 offset:53248
	v_lshl_add_u64 v[246:247], v[132:133], 0, s[50:51]
	s_add_i32 m0, s10, 0x8000
	s_nop 0
	global_load_lds_dwordx4 v[246:247], off
	v_lshl_add_u64 v[248:249], v[134:135], 0, s[50:51]
	s_add_i32 m0, s10, 0x8400
	s_nop 0
	global_load_lds_dwordx4 v[248:249], off
	v_lshl_add_u64 v[246:247], v[132:133], 0, s[50:51]
	v_lshl_add_u64 v[246:247], v[246:247], 0, s[54:55]
	s_add_i32 m0, s10, 0x8800
	s_nop 0
	global_load_lds_dwordx4 v[246:247], off
	v_lshl_add_u64 v[248:249], v[134:135], 0, s[50:51]
	v_lshl_add_u64 v[248:249], v[248:249], 0, s[54:55]
	s_add_i32 m0, s10, 0x8c00
	s_nop 0
	global_load_lds_dwordx4 v[248:249], off
	v_lshl_add_u64 v[246:247], v[128:129], 0, s[50:51]
	v_lshl_add_u64 v[246:247], v[246:247], 0, s[52:53]
	s_add_i32 m0, s63, 0x6000
	s_nop 0
	global_load_lds_dwordx4 v[246:247], off
	v_lshl_add_u64 v[248:249], v[130:131], 0, s[50:51]
	v_lshl_add_u64 v[248:249], v[248:249], 0, s[52:53]
	s_add_i32 m0, s63, 0x6400
	s_nop 0
	global_load_lds_dwordx4 v[248:249], off
	s_add_u32 s48, s48, 0x80
	s_addc_u32 s49, s49, 0
	s_add_u32 s50, s50, 0x80
	s_addc_u32 s51, s51, 0
	s_setprio 1
	s_waitcnt lgkmcnt(7)
	v_mfma_f32_32x32x16_bf16 v[32:47], v[188:191], v[140:143], v[32:47]
	s_waitcnt lgkmcnt(6)
	v_mfma_f32_32x32x16_bf16 v[48:63], v[204:207], v[140:143], v[48:63]
	v_mfma_f32_32x32x16_bf16 v[0:15], v[188:191], v[164:167], v[0:15]
	v_mfma_f32_32x32x16_bf16 v[16:31], v[204:207], v[164:167], v[16:31]
	s_waitcnt lgkmcnt(5)
	v_mfma_f32_32x32x16_bf16 v[32:47], v[192:195], v[144:147], v[32:47]
	s_waitcnt lgkmcnt(4)
	v_mfma_f32_32x32x16_bf16 v[48:63], v[208:211], v[144:147], v[48:63]
	v_mfma_f32_32x32x16_bf16 v[0:15], v[192:195], v[170:173], v[0:15]
	v_mfma_f32_32x32x16_bf16 v[16:31], v[208:211], v[170:173], v[16:31]
	s_waitcnt lgkmcnt(3)
	v_mfma_f32_32x32x16_bf16 v[32:47], v[196:199], v[148:151], v[32:47]
	s_waitcnt lgkmcnt(2)
	v_mfma_f32_32x32x16_bf16 v[48:63], v[238:241], v[148:151], v[48:63]
	v_mfma_f32_32x32x16_bf16 v[0:15], v[196:199], v[180:183], v[0:15]
	v_mfma_f32_32x32x16_bf16 v[16:31], v[238:241], v[180:183], v[16:31]
	s_waitcnt lgkmcnt(1)
	v_mfma_f32_32x32x16_bf16 v[32:47], v[200:203], v[160:163], v[32:47]
	s_waitcnt lgkmcnt(0)
	v_mfma_f32_32x32x16_bf16 v[48:63], v[242:245], v[160:163], v[48:63]
	v_mfma_f32_32x32x16_bf16 v[0:15], v[200:203], v[184:187], v[0:15]
	v_mfma_f32_32x32x16_bf16 v[16:31], v[242:245], v[184:187], v[16:31]
	s_setprio 0
	s_waitcnt vmcnt(0)
	s_barrier
	ds_read_b128 v[140:143], v136 offset:16384
	ds_read_b128 v[188:191], v232 offset:32768
	ds_read_b128 v[204:207], v232 offset:36864
	ds_read_b128 v[164:167], v136 offset:20480
	ds_read_b128 v[144:147], v137 offset:16384
	ds_read_b128 v[192:195], v233 offset:32768
	ds_read_b128 v[208:211], v233 offset:36864
	ds_read_b128 v[170:173], v137 offset:20480
	v_lshl_add_u64 v[246:247], v[132:133], 0, s[48:49]
	v_lshl_add_u64 v[246:247], v[246:247], 0, s[52:53]
	s_add_i32 m0, s10, 0xc000
	s_nop 0
	global_load_lds_dwordx4 v[246:247], off
	v_lshl_add_u64 v[248:249], v[134:135], 0, s[48:49]
	v_lshl_add_u64 v[248:249], v[248:249], 0, s[52:53]
	s_add_i32 m0, s10, 0xc400
	s_nop 0
	global_load_lds_dwordx4 v[248:249], off
	v_lshl_add_u64 v[246:247], v[132:133], 0, s[48:49]
	v_lshl_add_u64 v[246:247], v[246:247], 0, s[52:53]
	v_lshl_add_u64 v[246:247], v[246:247], 0, s[54:55]
	s_add_i32 m0, s10, 0xc800
	s_nop 0
	global_load_lds_dwordx4 v[246:247], off
	v_lshl_add_u64 v[248:249], v[134:135], 0, s[48:49]
	v_lshl_add_u64 v[248:249], v[248:249], 0, s[52:53]
	v_lshl_add_u64 v[248:249], v[248:249], 0, s[54:55]
	s_add_i32 m0, s10, 0xcc00
	s_nop 0
	global_load_lds_dwordx4 v[248:249], off
	v_lshl_add_u64 v[246:247], v[128:129], 0, s[50:51]
	s_add_i32 m0, s63, 0x0
	s_nop 0
	global_load_lds_dwordx4 v[246:247], off
	v_lshl_add_u64 v[248:249], v[130:131], 0, s[50:51]
	s_add_i32 m0, s63, 0x400
	s_nop 0
	global_load_lds_dwordx4 v[248:249], off
	s_setprio 1
	s_waitcnt lgkmcnt(6)
	v_mfma_f32_32x32x16_bf16 v[96:111], v[188:191], v[140:143], v[96:111]
	s_waitcnt lgkmcnt(5)
	v_mfma_f32_32x32x16_bf16 v[112:127], v[204:207], v[140:143], v[112:127]
	s_waitcnt lgkmcnt(4)
	v_mfma_f32_32x32x16_bf16 v[64:79], v[188:191], v[164:167], v[64:79]
	v_mfma_f32_32x32x16_bf16 v[80:95], v[204:207], v[164:167], v[80:95]
	ds_read_b128 v[148:151], v138 offset:16384
	ds_read_b128 v[196:199], v237 offset:32768
	ds_read_b128 v[238:241], v237 offset:36864
	ds_read_b128 v[180:183], v138 offset:20480
	s_waitcnt lgkmcnt(6)
	v_mfma_f32_32x32x16_bf16 v[96:111], v[192:195], v[144:147], v[96:111]
	s_waitcnt lgkmcnt(5)
	v_mfma_f32_32x32x16_bf16 v[112:127], v[208:211], v[144:147], v[112:127]
	s_waitcnt lgkmcnt(4)
	v_mfma_f32_32x32x16_bf16 v[64:79], v[192:195], v[170:173], v[64:79]
	v_mfma_f32_32x32x16_bf16 v[80:95], v[208:211], v[170:173], v[80:95]
	ds_read_b128 v[160:163], v139 offset:16384
	ds_read_b128 v[200:203], v252 offset:32768
	ds_read_b128 v[242:245], v252 offset:36864
	ds_read_b128 v[184:187], v139 offset:20480
	s_waitcnt lgkmcnt(6)
	v_mfma_f32_32x32x16_bf16 v[96:111], v[196:199], v[148:151], v[96:111]
	s_waitcnt lgkmcnt(5)
	v_mfma_f32_32x32x16_bf16 v[112:127], v[238:241], v[148:151], v[112:127]
	s_waitcnt lgkmcnt(4)
	v_mfma_f32_32x32x16_bf16 v[64:79], v[196:199], v[180:183], v[64:79]
	v_mfma_f32_32x32x16_bf16 v[80:95], v[238:241], v[180:183], v[80:95]
	s_waitcnt lgkmcnt(2)
	v_mfma_f32_32x32x16_bf16 v[96:111], v[200:203], v[160:163], v[96:111]
	s_waitcnt lgkmcnt(1)
	v_mfma_f32_32x32x16_bf16 v[112:127], v[242:245], v[160:163], v[112:127]
	s_waitcnt lgkmcnt(0)
	v_mfma_f32_32x32x16_bf16 v[64:79], v[200:203], v[184:187], v[64:79]
	v_mfma_f32_32x32x16_bf16 v[80:95], v[242:245], v[184:187], v[80:95]
	s_setprio 0
	s_waitcnt vmcnt(2)
	s_barrier
	ds_read_b128 v[188:191], v232 offset:49152
	ds_read_b128 v[204:207], v232 offset:53248
	ds_read_b128 v[192:195], v233 offset:49152
	ds_read_b128 v[208:211], v233 offset:53248
	ds_read_b128 v[196:199], v237 offset:49152
	ds_read_b128 v[238:241], v237 offset:53248
	ds_read_b128 v[200:203], v252 offset:49152
	ds_read_b128 v[242:245], v252 offset:53248
	v_lshl_add_u64 v[246:247], v[132:133], 0, s[50:51]
	s_add_i32 m0, s10, 0x8000
	s_nop 0
	global_load_lds_dwordx4 v[246:247], off
	v_lshl_add_u64 v[248:249], v[134:135], 0, s[50:51]
	s_add_i32 m0, s10, 0x8400
	s_nop 0
	global_load_lds_dwordx4 v[248:249], off
	v_lshl_add_u64 v[246:247], v[132:133], 0, s[50:51]
	v_lshl_add_u64 v[246:247], v[246:247], 0, s[54:55]
	s_add_i32 m0, s10, 0x8800
	s_nop 0
	global_load_lds_dwordx4 v[246:247], off
	v_lshl_add_u64 v[248:249], v[134:135], 0, s[50:51]
	v_lshl_add_u64 v[248:249], v[248:249], 0, s[54:55]
	s_add_i32 m0, s10, 0x8c00
	s_nop 0
	global_load_lds_dwordx4 v[248:249], off
	v_lshl_add_u64 v[246:247], v[128:129], 0, s[50:51]
	v_lshl_add_u64 v[246:247], v[246:247], 0, s[52:53]
	s_add_i32 m0, s63, 0x2000
	s_nop 0
	global_load_lds_dwordx4 v[246:247], off
	v_lshl_add_u64 v[248:249], v[130:131], 0, s[50:51]
	v_lshl_add_u64 v[248:249], v[248:249], 0, s[52:53]
	s_add_i32 m0, s63, 0x2400
	s_nop 0
	global_load_lds_dwordx4 v[248:249], off
	s_add_u32 s48, s48, 0x80
	s_addc_u32 s49, s49, 0
	s_add_u32 s50, s50, 0x80
	s_addc_u32 s51, s51, 0
	s_setprio 1
	s_waitcnt lgkmcnt(7)
	v_mfma_f32_32x32x16_bf16 v[32:47], v[188:191], v[140:143], v[32:47]
	s_waitcnt lgkmcnt(6)
	v_mfma_f32_32x32x16_bf16 v[48:63], v[204:207], v[140:143], v[48:63]
	v_mfma_f32_32x32x16_bf16 v[0:15], v[188:191], v[164:167], v[0:15]
	v_mfma_f32_32x32x16_bf16 v[16:31], v[204:207], v[164:167], v[16:31]
	s_waitcnt lgkmcnt(5)
	v_mfma_f32_32x32x16_bf16 v[32:47], v[192:195], v[144:147], v[32:47]
	s_waitcnt lgkmcnt(4)
	v_mfma_f32_32x32x16_bf16 v[48:63], v[208:211], v[144:147], v[48:63]
	v_mfma_f32_32x32x16_bf16 v[0:15], v[192:195], v[170:173], v[0:15]
	v_mfma_f32_32x32x16_bf16 v[16:31], v[208:211], v[170:173], v[16:31]
	s_waitcnt lgkmcnt(3)
	v_mfma_f32_32x32x16_bf16 v[32:47], v[196:199], v[148:151], v[32:47]
	s_waitcnt lgkmcnt(2)
	v_mfma_f32_32x32x16_bf16 v[48:63], v[238:241], v[148:151], v[48:63]
	v_mfma_f32_32x32x16_bf16 v[0:15], v[196:199], v[180:183], v[0:15]
	v_mfma_f32_32x32x16_bf16 v[16:31], v[238:241], v[180:183], v[16:31]
	s_waitcnt lgkmcnt(1)
	v_mfma_f32_32x32x16_bf16 v[32:47], v[200:203], v[160:163], v[32:47]
	s_waitcnt lgkmcnt(0)
	v_mfma_f32_32x32x16_bf16 v[48:63], v[242:245], v[160:163], v[48:63]
	v_mfma_f32_32x32x16_bf16 v[0:15], v[200:203], v[184:187], v[0:15]
	v_mfma_f32_32x32x16_bf16 v[16:31], v[242:245], v[184:187], v[16:31]
	s_setprio 0
	s_add_i32 s11, s11, -1
	s_cmp_lg_u32 s11, 0
	s_cbranch_scc1 .Lk3_loop
	s_waitcnt vmcnt(0)
	s_barrier
	ds_read_b128 v[140:143], v136 offset:0
	ds_read_b128 v[188:191], v232 offset:32768
	ds_read_b128 v[204:207], v232 offset:36864
	ds_read_b128 v[164:167], v136 offset:4096
	ds_read_b128 v[144:147], v137 offset:0
	ds_read_b128 v[192:195], v233 offset:32768
	ds_read_b128 v[208:211], v233 offset:36864
	ds_read_b128 v[170:173], v137 offset:4096
	v_lshl_add_u64 v[246:247], v[132:133], 0, s[48:49]
	v_lshl_add_u64 v[246:247], v[246:247], 0, s[52:53]
	s_add_i32 m0, s10, 0xc000
	s_nop 0
	global_load_lds_dwordx4 v[246:247], off
	v_lshl_add_u64 v[248:249], v[134:135], 0, s[48:49]
	v_lshl_add_u64 v[248:249], v[248:249], 0, s[52:53]
	s_add_i32 m0, s10, 0xc400
	s_nop 0
	global_load_lds_dwordx4 v[248:249], off
	v_lshl_add_u64 v[246:247], v[132:133], 0, s[48:49]
	v_lshl_add_u64 v[246:247], v[246:247], 0, s[52:53]
	v_lshl_add_u64 v[246:247], v[246:247], 0, s[54:55]
	s_add_i32 m0, s10, 0xc800
	s_nop 0
	global_load_lds_dwordx4 v[246:247], off
	v_lshl_add_u64 v[248:249], v[134:135], 0, s[48:49]
	v_lshl_add_u64 v[248:249], v[248:249], 0, s[52:53]
	v_lshl_add_u64 v[248:249], v[248:249], 0, s[54:55]
	s_add_i32 m0, s10, 0xcc00
	s_nop 0
	global_load_lds_dwordx4 v[248:249], off
	v_lshl_add_u64 v[246:247], v[128:129], 0, s[50:51]
	s_add_i32 m0, s63, 0x4000
	s_nop 0
	global_load_lds_dwordx4 v[246:247], off
	v_lshl_add_u64 v[248:249], v[130:131], 0, s[50:51]
	s_add_i32 m0, s63, 0x4400
	s_nop 0
	global_load_lds_dwordx4 v[248:249], off
	s_setprio 1
	s_waitcnt lgkmcnt(6)
	v_mfma_f32_32x32x16_bf16 v[96:111], v[188:191], v[140:143], v[96:111]
	s_waitcnt lgkmcnt(5)
	v_mfma_f32_32x32x16_bf16 v[112:127], v[204:207], v[140:143], v[112:127]
	s_waitcnt lgkmcnt(4)
	v_mfma_f32_32x32x16_bf16 v[64:79], v[188:191], v[164:167], v[64:79]
	v_mfma_f32_32x32x16_bf16 v[80:95], v[204:207], v[164:167], v[80:95]
	ds_read_b128 v[148:151], v138 offset:0
	ds_read_b128 v[196:199], v237 offset:32768
	ds_read_b128 v[238:241], v237 offset:36864
	ds_read_b128 v[180:183], v138 offset:4096
	s_waitcnt lgkmcnt(6)
	v_mfma_f32_32x32x16_bf16 v[96:111], v[192:195], v[144:147], v[96:111]
	s_waitcnt lgkmcnt(5)
	v_mfma_f32_32x32x16_bf16 v[112:127], v[208:211], v[144:147], v[112:127]
	s_waitcnt lgkmcnt(4)
	v_mfma_f32_32x32x16_bf16 v[64:79], v[192:195], v[170:173], v[64:79]
	v_mfma_f32_32x32x16_bf16 v[80:95], v[208:211], v[170:173], v[80:95]
	ds_read_b128 v[160:163], v139 offset:0
	ds_read_b128 v[200:203], v252 offset:32768
	ds_read_b128 v[242:245], v252 offset:36864
	ds_read_b128 v[184:187], v139 offset:4096
	s_waitcnt lgkmcnt(6)
	v_mfma_f32_32x32x16_bf16 v[96:111], v[196:199], v[148:151], v[96:111]
	s_waitcnt lgkmcnt(5)
	v_mfma_f32_32x32x16_bf16 v[112:127], v[238:241], v[148:151], v[112:127]
	s_waitcnt lgkmcnt(4)
	v_mfma_f32_32x32x16_bf16 v[64:79], v[196:199], v[180:183], v[64:79]
	v_mfma_f32_32x32x16_bf16 v[80:95], v[238:241], v[180:183], v[80:95]
	s_waitcnt lgkmcnt(2)
	v_mfma_f32_32x32x16_bf16 v[96:111], v[200:203], v[160:163], v[96:111]
	s_waitcnt lgkmcnt(1)
	v_mfma_f32_32x32x16_bf16 v[112:127], v[242:245], v[160:163], v[112:127]
	s_waitcnt lgkmcnt(0)
	v_mfma_f32_32x32x16_bf16 v[64:79], v[200:203], v[184:187], v[64:79]
	v_mfma_f32_32x32x16_bf16 v[80:95], v[242:245], v[184:187], v[80:95]
	s_setprio 0
	s_waitcnt vmcnt(2)
	s_barrier
	ds_read_b128 v[188:191], v232 offset:49152
	ds_read_b128 v[204:207], v232 offset:53248
	ds_read_b128 v[192:195], v233 offset:49152
	ds_read_b128 v[208:211], v233 offset:53248
	ds_read_b128 v[196:199], v237 offset:49152
	ds_read_b128 v[238:241], v237 offset:53248
	ds_read_b128 v[200:203], v252 offset:49152
	ds_read_b128 v[242:245], v252 offset:53248
	v_lshl_add_u64 v[246:247], v[132:133], 0, s[50:51]
	s_add_i32 m0, s10, 0x8000
	s_nop 0
	global_load_lds_dwordx4 v[246:247], off
	v_lshl_add_u64 v[248:249], v[134:135], 0, s[50:51]
	s_add_i32 m0, s10, 0x8400
	s_nop 0
	global_load_lds_dwordx4 v[248:249], off
	v_lshl_add_u64 v[246:247], v[132:133], 0, s[50:51]
	v_lshl_add_u64 v[246:247], v[246:247], 0, s[54:55]
	s_add_i32 m0, s10, 0x8800
	s_nop 0
	global_load_lds_dwordx4 v[246:247], off
	v_lshl_add_u64 v[248:249], v[134:135], 0, s[50:51]
	v_lshl_add_u64 v[248:249], v[248:249], 0, s[54:55]
	s_add_i32 m0, s10, 0x8c00
	s_nop 0
	global_load_lds_dwordx4 v[248:249], off
	v_lshl_add_u64 v[246:247], v[128:129], 0, s[50:51]
	v_lshl_add_u64 v[246:247], v[246:247], 0, s[52:53]
	s_add_i32 m0, s63, 0x6000
	s_nop 0
	global_load_lds_dwordx4 v[246:247], off
	v_lshl_add_u64 v[248:249], v[130:131], 0, s[50:51]
	v_lshl_add_u64 v[248:249], v[248:249], 0, s[52:53]
	s_add_i32 m0, s63, 0x6400
	s_nop 0
	global_load_lds_dwordx4 v[248:249], off
	s_add_u32 s48, s48, 0x80
	s_addc_u32 s49, s49, 0
	s_add_u32 s50, s50, 0x80
	s_addc_u32 s51, s51, 0
	s_setprio 1
	s_waitcnt lgkmcnt(7)
	v_mfma_f32_32x32x16_bf16 v[32:47], v[188:191], v[140:143], v[32:47]
	s_waitcnt lgkmcnt(6)
	v_mfma_f32_32x32x16_bf16 v[48:63], v[204:207], v[140:143], v[48:63]
	v_mfma_f32_32x32x16_bf16 v[0:15], v[188:191], v[164:167], v[0:15]
	v_mfma_f32_32x32x16_bf16 v[16:31], v[204:207], v[164:167], v[16:31]
	s_waitcnt lgkmcnt(5)
	v_mfma_f32_32x32x16_bf16 v[32:47], v[192:195], v[144:147], v[32:47]
	s_waitcnt lgkmcnt(4)
	v_mfma_f32_32x32x16_bf16 v[48:63], v[208:211], v[144:147], v[48:63]
	v_mfma_f32_32x32x16_bf16 v[0:15], v[192:195], v[170:173], v[0:15]
	v_mfma_f32_32x32x16_bf16 v[16:31], v[208:211], v[170:173], v[16:31]
	s_waitcnt lgkmcnt(3)
	v_mfma_f32_32x32x16_bf16 v[32:47], v[196:199], v[148:151], v[32:47]
	s_waitcnt lgkmcnt(2)
	v_mfma_f32_32x32x16_bf16 v[48:63], v[238:241], v[148:151], v[48:63]
	v_mfma_f32_32x32x16_bf16 v[0:15], v[196:199], v[180:183], v[0:15]
	v_mfma_f32_32x32x16_bf16 v[16:31], v[238:241], v[180:183], v[16:31]
	s_waitcnt lgkmcnt(1)
	v_mfma_f32_32x32x16_bf16 v[32:47], v[200:203], v[160:163], v[32:47]
	s_waitcnt lgkmcnt(0)
	v_mfma_f32_32x32x16_bf16 v[48:63], v[242:245], v[160:163], v[48:63]
	v_mfma_f32_32x32x16_bf16 v[0:15], v[200:203], v[184:187], v[0:15]
	v_mfma_f32_32x32x16_bf16 v[16:31], v[242:245], v[184:187], v[16:31]
	s_setprio 0
	s_waitcnt vmcnt(0)
	s_barrier
	ds_read_b128 v[140:143], v136 offset:16384
	ds_read_b128 v[188:191], v232 offset:32768
	ds_read_b128 v[204:207], v232 offset:36864
	ds_read_b128 v[164:167], v136 offset:20480
	ds_read_b128 v[144:147], v137 offset:16384
	ds_read_b128 v[192:195], v233 offset:32768
	ds_read_b128 v[208:211], v233 offset:36864
	ds_read_b128 v[170:173], v137 offset:20480
	v_lshl_add_u64 v[246:247], v[132:133], 0, s[48:49]
	v_lshl_add_u64 v[246:247], v[246:247], 0, s[52:53]
	s_add_i32 m0, s10, 0xc000
	s_nop 0
	global_load_lds_dwordx4 v[246:247], off
	v_lshl_add_u64 v[248:249], v[134:135], 0, s[48:49]
	v_lshl_add_u64 v[248:249], v[248:249], 0, s[52:53]
	s_add_i32 m0, s10, 0xc400
	s_nop 0
	global_load_lds_dwordx4 v[248:249], off
	v_lshl_add_u64 v[246:247], v[132:133], 0, s[48:49]
	v_lshl_add_u64 v[246:247], v[246:247], 0, s[52:53]
	v_lshl_add_u64 v[246:247], v[246:247], 0, s[54:55]
	s_add_i32 m0, s10, 0xc800
	s_nop 0
	global_load_lds_dwordx4 v[246:247], off
	v_lshl_add_u64 v[248:249], v[134:135], 0, s[48:49]
	v_lshl_add_u64 v[248:249], v[248:249], 0, s[52:53]
	v_lshl_add_u64 v[248:249], v[248:249], 0, s[54:55]
	s_add_i32 m0, s10, 0xcc00
	s_nop 0
	global_load_lds_dwordx4 v[248:249], off
	s_setprio 1
	s_waitcnt lgkmcnt(6)
	v_mfma_f32_32x32x16_bf16 v[96:111], v[188:191], v[140:143], v[96:111]
	s_waitcnt lgkmcnt(5)
	v_mfma_f32_32x32x16_bf16 v[112:127], v[204:207], v[140:143], v[112:127]
	s_waitcnt lgkmcnt(4)
	v_mfma_f32_32x32x16_bf16 v[64:79], v[188:191], v[164:167], v[64:79]
	v_mfma_f32_32x32x16_bf16 v[80:95], v[204:207], v[164:167], v[80:95]
	ds_read_b128 v[148:151], v138 offset:16384
	ds_read_b128 v[196:199], v237 offset:32768
	ds_read_b128 v[238:241], v237 offset:36864
	ds_read_b128 v[180:183], v138 offset:20480
	s_waitcnt lgkmcnt(6)
	v_mfma_f32_32x32x16_bf16 v[96:111], v[192:195], v[144:147], v[96:111]
	s_waitcnt lgkmcnt(5)
	v_mfma_f32_32x32x16_bf16 v[112:127], v[208:211], v[144:147], v[112:127]
	s_waitcnt lgkmcnt(4)
	v_mfma_f32_32x32x16_bf16 v[64:79], v[192:195], v[170:173], v[64:79]
	v_mfma_f32_32x32x16_bf16 v[80:95], v[208:211], v[170:173], v[80:95]
	ds_read_b128 v[160:163], v139 offset:16384
	ds_read_b128 v[200:203], v252 offset:32768
	ds_read_b128 v[242:245], v252 offset:36864
	ds_read_b128 v[184:187], v139 offset:20480
	s_waitcnt lgkmcnt(6)
	v_mfma_f32_32x32x16_bf16 v[96:111], v[196:199], v[148:151], v[96:111]
	s_waitcnt lgkmcnt(5)
	v_mfma_f32_32x32x16_bf16 v[112:127], v[238:241], v[148:151], v[112:127]
	s_waitcnt lgkmcnt(4)
	v_mfma_f32_32x32x16_bf16 v[64:79], v[196:199], v[180:183], v[64:79]
	v_mfma_f32_32x32x16_bf16 v[80:95], v[238:241], v[180:183], v[80:95]
	s_waitcnt lgkmcnt(2)
	v_mfma_f32_32x32x16_bf16 v[96:111], v[200:203], v[160:163], v[96:111]
	s_waitcnt lgkmcnt(1)
	v_mfma_f32_32x32x16_bf16 v[112:127], v[242:245], v[160:163], v[112:127]
	s_waitcnt lgkmcnt(0)
	v_mfma_f32_32x32x16_bf16 v[64:79], v[200:203], v[184:187], v[64:79]
	v_mfma_f32_32x32x16_bf16 v[80:95], v[242:245], v[184:187], v[80:95]
	s_setprio 0
	s_waitcnt vmcnt(0)
	s_barrier
	ds_read_b128 v[188:191], v232 offset:49152
	ds_read_b128 v[204:207], v232 offset:53248
	ds_read_b128 v[192:195], v233 offset:49152
	ds_read_b128 v[208:211], v233 offset:53248
	ds_read_b128 v[196:199], v237 offset:49152
	ds_read_b128 v[238:241], v237 offset:53248
	ds_read_b128 v[200:203], v252 offset:49152
	ds_read_b128 v[242:245], v252 offset:53248
	s_setprio 1
	s_waitcnt lgkmcnt(7)
	v_mfma_f32_32x32x16_bf16 v[32:47], v[188:191], v[140:143], v[32:47]
	s_waitcnt lgkmcnt(6)
	v_mfma_f32_32x32x16_bf16 v[48:63], v[204:207], v[140:143], v[48:63]
	v_mfma_f32_32x32x16_bf16 v[0:15], v[188:191], v[164:167], v[0:15]
	v_mfma_f32_32x32x16_bf16 v[16:31], v[204:207], v[164:167], v[16:31]
	s_waitcnt lgkmcnt(5)
	v_mfma_f32_32x32x16_bf16 v[32:47], v[192:195], v[144:147], v[32:47]
	s_waitcnt lgkmcnt(4)
	v_mfma_f32_32x32x16_bf16 v[48:63], v[208:211], v[144:147], v[48:63]
	v_mfma_f32_32x32x16_bf16 v[0:15], v[192:195], v[170:173], v[0:15]
	v_mfma_f32_32x32x16_bf16 v[16:31], v[208:211], v[170:173], v[16:31]
	s_waitcnt lgkmcnt(3)
	v_mfma_f32_32x32x16_bf16 v[32:47], v[196:199], v[148:151], v[32:47]
	s_waitcnt lgkmcnt(2)
	v_mfma_f32_32x32x16_bf16 v[48:63], v[238:241], v[148:151], v[48:63]
	v_mfma_f32_32x32x16_bf16 v[0:15], v[196:199], v[180:183], v[0:15]
	v_mfma_f32_32x32x16_bf16 v[16:31], v[238:241], v[180:183], v[16:31]
	s_waitcnt lgkmcnt(1)
	v_mfma_f32_32x32x16_bf16 v[32:47], v[200:203], v[160:163], v[32:47]
	s_waitcnt lgkmcnt(0)
	v_mfma_f32_32x32x16_bf16 v[48:63], v[242:245], v[160:163], v[48:63]
	v_mfma_f32_32x32x16_bf16 v[0:15], v[200:203], v[184:187], v[0:15]
	v_mfma_f32_32x32x16_bf16 v[16:31], v[242:245], v[184:187], v[16:31]
	s_setprio 0
	s_branch .LBB0_770
